# speedup vs baseline: 1.0120x; 1.0120x over previous
.Lcoldzero_0:
	v_mov_b32_e32 v126, v127
	v_mov_b32_e32 v125, v127
	v_mov_b32_e32 v124, v127
	v_mov_b32_e32 v123, v127
	v_mov_b32_e32 v122, v127
	v_mov_b32_e32 v121, v127
	v_mov_b32_e32 v120, v127
	v_mov_b32_e32 v111, v127
	v_mov_b32_e32 v110, v127
	v_mov_b32_e32 v109, v127
	v_mov_b32_e32 v108, v127
	v_mov_b32_e32 v107, v127
	v_mov_b32_e32 v106, v127
	v_mov_b32_e32 v105, v127
	v_mov_b32_e32 v104, v127
	v_mov_b32_e32 v95, v127
	v_mov_b32_e32 v94, v127
	v_mov_b32_e32 v93, v127
	v_mov_b32_e32 v92, v127
	v_mov_b32_e32 v91, v127
	v_mov_b32_e32 v90, v127
	v_mov_b32_e32 v89, v127
	v_mov_b32_e32 v88, v127
	v_mov_b32_e32 v79, v127
	v_mov_b32_e32 v78, v127
	v_mov_b32_e32 v77, v127
	v_mov_b32_e32 v76, v127
	v_mov_b32_e32 v75, v127
	v_mov_b32_e32 v74, v127
	v_mov_b32_e32 v73, v127
	v_mov_b32_e32 v72, v127
	v_mov_b32_e32 v119, v127
	v_mov_b32_e32 v118, v127
	v_mov_b32_e32 v117, v127
	v_mov_b32_e32 v116, v127
	v_mov_b32_e32 v115, v127
	v_mov_b32_e32 v114, v127
	v_mov_b32_e32 v113, v127
	v_mov_b32_e32 v112, v127
	v_mov_b32_e32 v103, v127
	v_mov_b32_e32 v102, v127
	v_mov_b32_e32 v101, v127
	v_mov_b32_e32 v100, v127
	v_mov_b32_e32 v99, v127
	v_mov_b32_e32 v98, v127
	v_mov_b32_e32 v97, v127
	v_mov_b32_e32 v96, v127
	v_mov_b32_e32 v87, v127
	v_mov_b32_e32 v86, v127
	v_mov_b32_e32 v85, v127
	v_mov_b32_e32 v84, v127
	v_mov_b32_e32 v83, v127
	v_mov_b32_e32 v82, v127
	v_mov_b32_e32 v81, v127
	v_mov_b32_e32 v80, v127
	v_mov_b32_e32 v71, v127
	v_mov_b32_e32 v70, v127
	v_mov_b32_e32 v69, v127
	v_mov_b32_e32 v68, v127
	v_mov_b32_e32 v67, v127
	v_mov_b32_e32 v66, v127
	v_mov_b32_e32 v65, v127
	v_mov_b32_e32 v64, v127
	v_mov_b32_e32 v63, v127
	v_mov_b32_e32 v62, v127
	v_mov_b32_e32 v61, v127
	v_mov_b32_e32 v60, v127
	v_mov_b32_e32 v59, v127
	v_mov_b32_e32 v58, v127
	v_mov_b32_e32 v57, v127
	v_mov_b32_e32 v56, v127
	v_mov_b32_e32 v47, v127
	v_mov_b32_e32 v46, v127
	v_mov_b32_e32 v45, v127
	v_mov_b32_e32 v44, v127
	v_mov_b32_e32 v43, v127
	v_mov_b32_e32 v42, v127
	v_mov_b32_e32 v41, v127
	v_mov_b32_e32 v40, v127
	v_mov_b32_e32 v31, v127
	v_mov_b32_e32 v30, v127
	v_mov_b32_e32 v29, v127
	v_mov_b32_e32 v28, v127
	v_mov_b32_e32 v27, v127
	v_mov_b32_e32 v26, v127
	v_mov_b32_e32 v25, v127
	v_mov_b32_e32 v24, v127
	v_mov_b32_e32 v15, v127
	v_mov_b32_e32 v14, v127
	v_mov_b32_e32 v13, v127
	v_mov_b32_e32 v12, v127
	v_mov_b32_e32 v11, v127
	v_mov_b32_e32 v10, v127
	v_mov_b32_e32 v9, v127
	v_mov_b32_e32 v8, v127
	v_mov_b32_e32 v55, v127
	v_mov_b32_e32 v54, v127
	v_mov_b32_e32 v53, v127
	v_mov_b32_e32 v52, v127
	v_mov_b32_e32 v51, v127
	v_mov_b32_e32 v50, v127
	v_mov_b32_e32 v49, v127
	v_mov_b32_e32 v48, v127
	v_mov_b32_e32 v39, v127
	v_mov_b32_e32 v38, v127
	v_mov_b32_e32 v37, v127
	v_mov_b32_e32 v36, v127
	v_mov_b32_e32 v35, v127
	v_mov_b32_e32 v34, v127
	v_mov_b32_e32 v33, v127
	v_mov_b32_e32 v32, v127
	v_mov_b32_e32 v23, v127
	v_mov_b32_e32 v22, v127
	v_mov_b32_e32 v21, v127
	v_mov_b32_e32 v20, v127
	v_mov_b32_e32 v19, v127
	v_mov_b32_e32 v18, v127
	v_mov_b32_e32 v17, v127
	v_mov_b32_e32 v16, v127
	v_mov_b32_e32 v7, v127
	v_mov_b32_e32 v6, v127
	v_mov_b32_e32 v5, v127
	v_mov_b32_e32 v4, v127
	v_mov_b32_e32 v3, v127
	v_mov_b32_e32 v2, v127
	v_mov_b32_e32 v1, v127
	v_mov_b32_e32 v0, v127
	s_branch .LBB0_214

.LBB0_211:
	v_readlane_b32 s30, v255, 2
	v_readlane_b32 s31, v255, 3
	s_add_u32 s3, s30, s26
	s_addc_u32 s17, s31, s27
	s_and_b64 s[30:31], s[4:5], exec
	v_readlane_b32 s34, v255, 50
	s_cselect_b32 s31, s17, s7
	s_cselect_b32 s30, s3, s6
	v_readlane_b32 s35, v255, 51
	s_add_u32 s3, s34, s28
	s_addc_u32 s17, s35, s29
	s_and_b64 s[34:35], s[4:5], exec
	v_mov_b32_e32 v127, 0
	s_cselect_b32 s35, s17, s37
	s_cselect_b32 s34, s3, s36
	s_andn2_b64 vcc, exec, s[14:15]
	s_cbranch_vccnz .Lcoldzero_0
	v_mov_b64_e32 v[0:1], 0
	s_mov_b32 s3, 0
	s_mov_b64 s[54:55], 0
	v_mov_b64_e32 v[2:3], 0
	v_mov_b64_e32 v[4:5], 0
	v_mov_b64_e32 v[6:7], 0
	v_mov_b64_e32 v[8:9], 0
	v_mov_b64_e32 v[10:11], 0
	v_mov_b64_e32 v[12:13], 0
	v_mov_b64_e32 v[14:15], 0
	v_mov_b64_e32 v[16:17], 0
	v_mov_b64_e32 v[18:19], 0
	v_mov_b64_e32 v[20:21], 0
	v_mov_b64_e32 v[22:23], 0
	v_mov_b64_e32 v[24:25], 0
	v_mov_b64_e32 v[26:27], 0
	v_mov_b64_e32 v[28:29], 0
	v_mov_b64_e32 v[30:31], 0
	v_mov_b64_e32 v[32:33], 0
	v_mov_b64_e32 v[34:35], 0
	v_mov_b64_e32 v[36:37], 0
	v_mov_b64_e32 v[38:39], 0
	v_mov_b64_e32 v[40:41], 0
	v_mov_b64_e32 v[42:43], 0
	v_mov_b64_e32 v[44:45], 0
	v_mov_b64_e32 v[46:47], 0
	v_mov_b64_e32 v[48:49], 0
	v_mov_b64_e32 v[50:51], 0
	v_mov_b64_e32 v[52:53], 0
	v_mov_b64_e32 v[54:55], 0
	v_mov_b64_e32 v[56:57], 0
	v_mov_b64_e32 v[58:59], 0
	v_mov_b64_e32 v[60:61], 0
	v_mov_b64_e32 v[62:63], 0
	v_mov_b64_e32 v[64:65], 0
	v_mov_b64_e32 v[66:67], 0
	v_mov_b64_e32 v[68:69], 0
	v_mov_b64_e32 v[70:71], 0
	v_mov_b64_e32 v[72:73], 0
	v_mov_b64_e32 v[74:75], 0
	v_mov_b64_e32 v[76:77], 0
	v_mov_b64_e32 v[78:79], 0
	v_mov_b64_e32 v[80:81], 0
	v_mov_b64_e32 v[82:83], 0
	v_mov_b64_e32 v[84:85], 0
	v_mov_b64_e32 v[86:87], 0
	v_mov_b64_e32 v[88:89], 0
	v_mov_b64_e32 v[90:91], 0
	v_mov_b64_e32 v[92:93], 0
	v_mov_b64_e32 v[94:95], 0
	v_mov_b64_e32 v[96:97], 0
	v_mov_b64_e32 v[98:99], 0
	v_mov_b64_e32 v[100:101], 0
	v_mov_b64_e32 v[102:103], 0
	v_mov_b64_e32 v[104:105], 0
	v_mov_b64_e32 v[106:107], 0
	v_mov_b64_e32 v[108:109], 0
	v_mov_b64_e32 v[110:111], 0
	v_mov_b64_e32 v[112:113], 0
	v_mov_b64_e32 v[114:115], 0
	v_mov_b64_e32 v[116:117], 0
	v_mov_b64_e32 v[118:119], 0
	v_mov_b64_e32 v[120:121], 0
	v_mov_b64_e32 v[122:123], 0
	v_mov_b64_e32 v[124:125], 0
	v_mov_b64_e32 v[126:127], 0

.LBB0_296:
	v_readlane_b32 s36, v254, 43
	s_sub_i32 s4, 0x7ff, s29
	s_mov_b32 s5, s13
	v_readlane_b32 s50, v254, 57
	v_readlane_b32 s51, v254, 58
	s_lshl_b64 s[2:3], s[4:5], 2
	s_mov_b64 s[66:67], s[50:51]
	v_readlane_b32 s37, v254, 44
	s_add_u32 s6, s66, s2
	v_mov_b32_e32 v42, v180
	v_readlane_b32 s38, v254, 45
	v_readlane_b32 s39, v254, 46
	v_readlane_b32 s40, v254, 47
	v_readlane_b32 s41, v254, 48
	v_readlane_b32 s42, v254, 49
	v_readlane_b32 s43, v254, 50
	v_readlane_b32 s44, v254, 51
	v_readlane_b32 s45, v254, 52
	v_readlane_b32 s46, v254, 53
	v_readlane_b32 s47, v254, 54
	v_readlane_b32 s48, v254, 55
	v_readlane_b32 s49, v254, 56
	s_mov_b64 s[52:53], s[36:37]
	s_addc_u32 s7, s67, s3
	v_mov_b32_e32 v0, 0x2000
	global_load_dword v2, v1, s[6:7]
	global_load_dword v4, v0, s[6:7]
	s_add_u32 s6, s52, s2
	v_readlane_b32 s36, v254, 9
	s_addc_u32 s7, s53, s3
	v_readlane_b32 s50, v254, 23
	global_load_dword v6, v1, s[6:7]
	v_readlane_b32 s51, v254, 24
	s_add_u32 s6, s50, s2
	s_addc_u32 s7, s51, s3
	s_sub_i32 s12, 0xfff, s29
	s_lshl_b64 s[2:3], s[12:13], 2
	s_add_u32 s16, s52, s2
	s_addc_u32 s17, s53, s3
	s_add_u32 s2, s50, s2
	v_mov_b32_e32 v0, 0x6000
	s_addc_u32 s3, s51, s3
	global_load_dword v8, v0, s[6:7]
	global_load_dword v12, v1, s[16:17]
	global_load_dword v15, v1, s[2:3]
	s_sub_i32 s2, 0x17ff, s29
	s_mov_b32 s3, s13
	s_lshl_b64 s[16:17], s[2:3], 2
	v_readlane_b32 s37, v254, 10
	s_add_u32 s36, s52, s16
	s_addc_u32 s37, s53, s17
	s_add_u32 s16, s50, s16
	v_mov_b32_e32 v0, 0xc000
	s_addc_u32 s17, s51, s17
	global_load_dword v9, v1, s[6:7]
	global_load_dword v18, v1, s[36:37]
	global_load_dword v21, v1, s[16:17]
	global_load_dword v10, v0, s[6:7]
	v_mov_b32_e32 v0, 0x8000
	global_load_dword v14, v0, s[6:7]
	v_mov_b32_e32 v0, 0xe000
	global_load_dword v16, v0, s[6:7]
	v_mov_b32_e32 v0, 0xa000
	global_load_dword v20, v0, s[6:7]
	v_mov_b32_e32 v0, 0x10000
	v_ashrrev_i32_e32 v43, 31, v42
	global_load_dword v22, v0, s[6:7]
	v_lshrrev_b32_e32 v0, 23, v43
	v_add_u32_e32 v0, v42, v0
	v_and_b32_e32 v0, 0xfffffe00, v0
	v_sub_u32_e32 v3, v42, v0
	s_mul_i32 s68, s4, 0xa000
	v_lshlrev_b32_e32 v112, 2, v3
	s_mul_hi_u32 s25, s4, 0xa000
	s_add_u32 s74, s20, s68
	v_ashrrev_i32_e32 v113, 31, v112
	s_addc_u32 s75, s21, s25
	v_lshl_add_u64 v[24:25], v[112:113], 1, s[74:75]
	v_add_co_u32_e32 v26, vcc, 0x2000, v24
	v_cmp_lt_i32_e64 s[4:5], 0, v3
	s_nop 0
	v_addc_co_u32_e32 v27, vcc, 0, v25, vcc
	global_load_dwordx2 v[46:47], v[26:27], off
	v_lshl_add_u64 v[24:25], v[24:25], 0, s[14:15]
	v_mov_b32_e32 v49, v1
	v_readlane_b32 s38, v254, 11
	v_readlane_b32 s39, v254, 12
	v_readlane_b32 s40, v254, 13
	v_readlane_b32 s41, v254, 14
	v_readlane_b32 s42, v254, 15
	v_readlane_b32 s43, v254, 16
	v_readlane_b32 s44, v254, 17
	v_readlane_b32 s45, v254, 18
	v_readlane_b32 s46, v254, 19
	v_readlane_b32 s47, v254, 20
	v_readlane_b32 s48, v254, 21
	v_readlane_b32 s49, v254, 22
	s_and_saveexec_b64 s[6:7], s[4:5]
	s_cbranch_execz .LBB0_298
	global_load_ushort v49, v[24:25], off offset:-2
.LBB0_298:
	s_or_b64 exec, exec, s[6:7]
	s_movk_i32 s3, 0x1ff
	v_cmp_ne_u32_e64 s[6:7], s3, v3
	v_mov_b32_e32 v51, 0
	v_mov_b32_e32 v45, 0
	s_and_saveexec_b64 s[16:17], s[6:7]
	s_cbranch_execz .LBB0_300
	global_load_ushort v45, v[24:25], off offset:8
.LBB0_300:
	s_or_b64 exec, exec, s[16:17]
	s_mul_i32 s11, s12, 0xa000
	s_mul_hi_u32 s9, s12, 0xa000
	s_add_u32 s76, s20, s11
	s_addc_u32 s77, s21, s9
	v_lshl_add_u64 v[24:25], v[112:113], 1, s[76:77]
	v_add_co_u32_e32 v26, vcc, 0x2000, v24
	s_nop 1
	v_addc_co_u32_e32 v27, vcc, 0, v25, vcc
	global_load_dwordx2 v[52:53], v[26:27], off
	v_lshl_add_u64 v[24:25], v[24:25], 0, s[14:15]
	s_and_saveexec_b64 s[16:17], s[4:5]
	s_cbranch_execz .LBB0_302
	global_load_ushort v51, v[24:25], off offset:-2
.LBB0_302:
	s_or_b64 exec, exec, s[16:17]
	v_mov_b32_e32 v57, 0
	v_mov_b32_e32 v55, 0
	s_and_saveexec_b64 s[16:17], s[6:7]
	s_cbranch_execz .LBB0_304
	global_load_ushort v55, v[24:25], off offset:8
.LBB0_304:
	s_or_b64 exec, exec, s[16:17]
	s_mul_i32 s35, s2, 0xa000
	s_mul_hi_u32 s12, s2, 0xa000
	s_add_u32 s78, s20, s35
	s_addc_u32 s79, s21, s12
	v_lshl_add_u64 v[24:25], v[112:113], 1, s[78:79]
	v_add_co_u32_e32 v26, vcc, 0x2000, v24
	s_nop 1
	v_addc_co_u32_e32 v27, vcc, 0, v25, vcc
	global_load_dwordx2 v[58:59], v[26:27], off
	v_lshl_add_u64 v[24:25], v[24:25], 0, s[14:15]
	s_and_saveexec_b64 s[2:3], s[4:5]
	s_cbranch_execz .LBB0_306
	global_load_ushort v57, v[24:25], off offset:-2
.LBB0_306:
	s_or_b64 exec, exec, s[2:3]
	v_mov_b32_e32 v63, 0
	v_mov_b32_e32 v61, 0
	s_and_saveexec_b64 s[2:3], s[6:7]
	s_cbranch_execz .LBB0_308
	global_load_ushort v61, v[24:25], off offset:8
.LBB0_308:
	s_or_b64 exec, exec, s[2:3]
	s_add_u32 s80, s69, s68
	s_addc_u32 s81, s70, s25
	v_lshl_add_u64 v[24:25], v[112:113], 1, s[80:81]
	v_add_co_u32_e32 v26, vcc, 0x2000, v24
	s_nop 1
	v_addc_co_u32_e32 v27, vcc, 0, v25, vcc
	global_load_dwordx2 v[64:65], v[26:27], off
	v_lshl_add_u64 v[24:25], v[24:25], 0, s[14:15]
	s_and_saveexec_b64 s[2:3], s[4:5]
	s_cbranch_execz .LBB0_310
	global_load_ushort v63, v[24:25], off offset:-2
.LBB0_310:
	s_or_b64 exec, exec, s[2:3]
	v_mov_b32_e32 v69, 0
	v_mov_b32_e32 v67, 0
	s_and_saveexec_b64 s[2:3], s[6:7]
	s_cbranch_execz .LBB0_312
	global_load_ushort v67, v[24:25], off offset:8
.LBB0_312:
	s_or_b64 exec, exec, s[2:3]
	s_add_u32 s96, s69, s11
	s_addc_u32 s97, s70, s9
	v_lshl_add_u64 v[24:25], v[112:113], 1, s[96:97]
	v_add_co_u32_e32 v26, vcc, 0x2000, v24
	s_nop 1
	v_addc_co_u32_e32 v27, vcc, 0, v25, vcc
	global_load_dwordx2 v[70:71], v[26:27], off
	v_lshl_add_u64 v[24:25], v[24:25], 0, s[14:15]
	s_and_saveexec_b64 s[2:3], s[4:5]
	s_cbranch_execz .LBB0_314
	global_load_ushort v69, v[24:25], off offset:-2
.LBB0_314:
	s_or_b64 exec, exec, s[2:3]
	v_mov_b32_e32 v75, 0
	v_mov_b32_e32 v73, 0
	s_and_saveexec_b64 s[2:3], s[6:7]
	s_cbranch_execz .LBB0_316
	global_load_ushort v73, v[24:25], off offset:8
.LBB0_316:
	s_or_b64 exec, exec, s[2:3]
	s_add_u32 s54, s69, s35
	s_addc_u32 s55, s70, s12
	v_lshl_add_u64 v[24:25], v[112:113], 1, s[54:55]
	v_add_co_u32_e32 v26, vcc, 0x2000, v24
	s_nop 1
	v_addc_co_u32_e32 v27, vcc, 0, v25, vcc
	global_load_dwordx2 v[76:77], v[26:27], off
	v_lshl_add_u64 v[24:25], v[24:25], 0, s[14:15]
	s_and_saveexec_b64 s[2:3], s[4:5]
	s_cbranch_execz .LBB0_318
	global_load_ushort v75, v[24:25], off offset:-2
.LBB0_318:
	s_or_b64 exec, exec, s[2:3]
	v_mov_b32_e32 v81, 0
	v_mov_b32_e32 v79, 0
	s_and_saveexec_b64 s[2:3], s[6:7]
	s_cbranch_execz .LBB0_320
	global_load_ushort v79, v[24:25], off offset:8
.LBB0_320:
	s_or_b64 exec, exec, s[2:3]
	s_add_u32 s58, s31, s68
	s_addc_u32 s59, s63, s25
	v_lshl_add_u64 v[24:25], v[112:113], 1, s[58:59]
	v_add_co_u32_e32 v26, vcc, 0x2000, v24
	s_nop 1
	v_addc_co_u32_e32 v27, vcc, 0, v25, vcc
	global_load_dwordx2 v[84:85], v[26:27], off
	v_lshl_add_u64 v[24:25], v[24:25], 0, s[14:15]
	s_and_saveexec_b64 s[2:3], s[4:5]
	s_cbranch_execz .LBB0_322
	global_load_ushort v81, v[24:25], off offset:-2
.LBB0_322:
	s_or_b64 exec, exec, s[2:3]
	v_mov_b32_e32 v89, 0
	v_mov_b32_e32 v87, 0
	s_and_saveexec_b64 s[2:3], s[6:7]
	s_cbranch_execz .LBB0_324
	global_load_ushort v87, v[24:25], off offset:8
.LBB0_324:
	s_or_b64 exec, exec, s[2:3]
	s_add_u32 s16, s31, s11
	s_addc_u32 s17, s63, s9
	v_lshl_add_u64 v[24:25], v[112:113], 1, s[16:17]
	v_add_co_u32_e32 v26, vcc, 0x2000, v24
	s_nop 1
	v_addc_co_u32_e32 v27, vcc, 0, v25, vcc
	global_load_dwordx2 v[90:91], v[26:27], off
	v_lshl_add_u64 v[24:25], v[24:25], 0, s[14:15]
	s_and_saveexec_b64 s[2:3], s[4:5]
	s_cbranch_execz .LBB0_326
	global_load_ushort v89, v[24:25], off offset:-2
.LBB0_326:
	s_or_b64 exec, exec, s[2:3]
	v_mov_b32_e32 v95, 0
	v_mov_b32_e32 v93, 0
	s_and_saveexec_b64 s[2:3], s[6:7]
	s_cbranch_execz .LBB0_328
	global_load_ushort v93, v[24:25], off offset:8
.LBB0_328:
	s_or_b64 exec, exec, s[2:3]
	s_add_u32 s36, s31, s35
	s_addc_u32 s37, s63, s12
	v_lshl_add_u64 v[24:25], v[112:113], 1, s[36:37]
	v_add_co_u32_e32 v26, vcc, 0x2000, v24
	s_nop 1
	v_addc_co_u32_e32 v27, vcc, 0, v25, vcc
	global_load_dwordx2 v[98:99], v[26:27], off
	v_lshl_add_u64 v[24:25], v[24:25], 0, s[14:15]
	s_and_saveexec_b64 s[2:3], s[4:5]
	s_cbranch_execz .LBB0_330
	global_load_ushort v95, v[24:25], off offset:-2
.LBB0_330:
	s_or_b64 exec, exec, s[2:3]
	v_mov_b32_e32 v103, 0
	v_mov_b32_e32 v101, 0
	s_and_saveexec_b64 s[2:3], s[6:7]
	s_cbranch_execz .LBB0_332
	global_load_ushort v101, v[24:25], off offset:8
.LBB0_332:
	s_or_b64 exec, exec, s[2:3]
	s_add_u32 s92, s18, s68
	s_addc_u32 s93, s19, s25
	v_lshl_add_u64 v[24:25], v[112:113], 1, s[92:93]
	v_add_co_u32_e32 v26, vcc, 0x2000, v24
	s_nop 1
	v_addc_co_u32_e32 v27, vcc, 0, v25, vcc
	global_load_dwordx2 v[36:37], v[26:27], off
	v_lshl_add_u64 v[24:25], v[24:25], 0, s[14:15]
	s_and_saveexec_b64 s[2:3], s[4:5]
	s_cbranch_execz .LBB0_334
	global_load_ushort v103, v[24:25], off offset:-2
.LBB0_334:
	s_or_b64 exec, exec, s[2:3]
	v_mov_b32_e32 v39, 0
	v_mov_b32_e32 v105, 0
	s_and_saveexec_b64 s[2:3], s[6:7]
	s_cbranch_execz .LBB0_336
	global_load_ushort v105, v[24:25], off offset:8
.LBB0_336:
	s_or_b64 exec, exec, s[2:3]
	s_add_u32 s2, s18, s11
	s_addc_u32 s3, s19, s9
	v_lshl_add_u64 v[24:25], v[112:113], 1, s[2:3]
	v_add_co_u32_e32 v26, vcc, 0x2000, v24
	s_nop 1
	v_addc_co_u32_e32 v27, vcc, 0, v25, vcc
	global_load_dwordx2 v[30:31], v[26:27], off
	v_lshl_add_u64 v[24:25], v[24:25], 0, s[14:15]
	s_and_saveexec_b64 s[88:89], s[4:5]
	s_cbranch_execz .LBB0_338
	global_load_ushort v39, v[24:25], off offset:-2
.LBB0_338:
	s_or_b64 exec, exec, s[88:89]
	v_mov_b32_e32 v33, 0
	v_mov_b32_e32 v41, 0
	s_and_saveexec_b64 s[88:89], s[6:7]
	s_cbranch_execz .LBB0_340
	global_load_ushort v41, v[24:25], off offset:8
.LBB0_340:
	s_or_b64 exec, exec, s[88:89]
	s_add_u32 s88, s18, s35
	s_addc_u32 s89, s19, s12
	v_lshl_add_u64 v[26:27], v[112:113], 1, s[88:89]
	v_add_co_u32_e32 v24, vcc, 0x2000, v26
	s_nop 1
	v_addc_co_u32_e32 v25, vcc, 0, v27, vcc
	global_load_dwordx2 v[24:25], v[24:25], off
	v_lshl_add_u64 v[26:27], v[26:27], 0, s[14:15]
	s_and_saveexec_b64 s[90:91], s[4:5]
	s_cbranch_execz .LBB0_342
	global_load_ushort v33, v[26:27], off offset:-2
.LBB0_342:
	s_or_b64 exec, exec, s[90:91]
	v_mov_b32_e32 v35, 0
	s_and_saveexec_b64 s[90:91], s[6:7]
	s_cbranch_execz .LBB0_344
	global_load_ushort v35, v[26:27], off offset:8
.LBB0_344:
	s_or_b64 exec, exec, s[90:91]
	s_waitcnt vmcnt(0)
	v_lshlrev_b32_e32 v49, 16, v49
	v_lshlrev_b32_e32 v45, 16, v45
	v_lshlrev_b32_e32 v51, 16, v51
	v_lshlrev_b32_e32 v55, 16, v55
	v_lshlrev_b32_e32 v57, 16, v57
	v_lshlrev_b32_e32 v61, 16, v61
	v_lshlrev_b32_e32 v63, 16, v63
	v_lshlrev_b32_e32 v67, 16, v67
	v_lshlrev_b32_e32 v69, 16, v69
	v_lshlrev_b32_e32 v73, 16, v73
	v_lshlrev_b32_e32 v75, 16, v75
	v_lshlrev_b32_e32 v79, 16, v79
	v_lshlrev_b32_e32 v81, 16, v81
	v_lshlrev_b32_e32 v87, 16, v87
	v_lshlrev_b32_e32 v89, 16, v89
	v_lshlrev_b32_e32 v93, 16, v93
	v_lshlrev_b32_e32 v95, 16, v95
	v_lshlrev_b32_e32 v101, 16, v101
	v_lshlrev_b32_e32 v103, 16, v103
	v_lshlrev_b32_e32 v105, 16, v105
	v_lshlrev_b32_e32 v39, 16, v39
	v_lshlrev_b32_e32 v41, 16, v41
	v_lshlrev_b32_e32 v33, 16, v33
	v_lshlrev_b32_e32 v35, 16, v35
	s_movk_i32 s9, 0x1000
	v_cmp_gt_i32_e32 vcc, s9, v42
	s_and_saveexec_b64 s[90:91], vcc
	s_cbranch_execz .LBB0_347
	s_mov_b32 s9, s13
	s_mov_b32 s11, s13
	s_lshl_b64 s[38:39], s[8:9], 14
	s_lshl_b64 s[40:41], s[10:11], 14
	v_readlane_b32 s42, v254, 60
	v_readlane_b32 s43, v254, 61
	s_add_u32 s38, s42, s38
	v_lshlrev_b64 v[28:29], 2, v[42:43]
	s_addc_u32 s39, s43, s39
	v_lshl_add_u64 v[26:27], s[38:39], 0, v[28:29]
	s_add_u32 s38, s42, s40
	s_addc_u32 s39, s43, s41
	v_lshl_add_u32 v5, v42, 3, 0
	v_lshl_add_u64 v[28:29], s[38:39], 0, v[28:29]
	s_mov_b64 s[94:95], 0
	v_mov_b32_e32 v7, v42

.LBB0_354:
	s_or_b64 exec, exec, s[2:3]
	s_waitcnt vmcnt(0)
	v_lshlrev_b32_e32 v197, 16, v197
	v_lshlrev_b32_e32 v163, 16, v163
	v_lshlrev_b32_e32 v199, 16, v199
	v_lshlrev_b32_e32 v183, 16, v183
	v_lshlrev_b32_e32 v201, 16, v201
	v_lshlrev_b32_e32 v177, 16, v177
	v_lshlrev_b32_e32 v203, 16, v203
	v_lshlrev_b32_e32 v195, 16, v195
	v_lshlrev_b32_e32 v205, 16, v205
	v_lshlrev_b32_e32 v173, 16, v173
	v_lshlrev_b32_e32 v207, 16, v207
	v_lshlrev_b32_e32 v169, 16, v169
	v_lshlrev_b32_e32 v213, 16, v213
	v_lshlrev_b32_e32 v191, 16, v191
	v_lshlrev_b32_e32 v217, 16, v217
	v_lshlrev_b32_e32 v161, 16, v161
	v_lshlrev_b32_e32 v219, 16, v219
	v_lshlrev_b32_e32 v157, 16, v157
	v_lshlrev_b32_e32 v221, 16, v221
	v_lshlrev_b32_e32 v187, 16, v187
	v_lshlrev_b32_e32 v223, 16, v223
	v_lshlrev_b32_e32 v97, 16, v97
	v_lshlrev_b32_e32 v211, 16, v211
	v_lshlrev_b32_e32 v209, 16, v209
	v_lshlrev_b32_e32 v215, 16, v225
	v_and_b32_e32 v208, 0xffff0000, v225
	v_and_b32_e32 v225, 0xffff0000, v82
	v_mov_b32_e32 v222, v225
	v_lshlrev_b32_e32 v226, 16, v224
	v_and_b32_e32 v214, 0xffff0000, v224
	v_lshlrev_b32_e32 v156, 16, v82
	v_lshlrev_b32_e32 v224, 16, v83
	v_and_b32_e32 v96, 0xffff0000, v83
	v_pk_mul_f32 v[82:83], v[14:15], v[222:223]
	v_pk_mul_f32 v[222:223], v[32:33], v[224:225]
	v_pk_fma_f32 v[82:83], v[30:31], v[156:157], v[82:83] op_sel_hi:[1,0,1]
	v_lshlrev_b32_e32 v156, 16, v184
	v_pk_fma_f32 v[82:83], v[16:17], v[224:225], v[82:83]
	v_mov_b32_e32 v225, v96
	v_pk_fma_f32 v[222:223], v[34:35], v[224:225], v[222:223] op_sel:[0,0,1] op_sel_hi:[1,1,0]
	v_and_b32_e32 v186, 0xffff0000, v185
	v_pk_fma_f32 v[96:97], v[16:17], v[96:97], v[222:223]
	v_and_b32_e32 v222, 0xffff0000, v184
	v_mov_b32_e32 v220, v222
	v_lshlrev_b32_e32 v223, 16, v185
	v_pk_mul_f32 v[184:185], v[8:9], v[220:221]
	v_pk_mul_f32 v[220:221], v[10:11], v[222:223]
	v_pk_fma_f32 v[184:185], v[36:37], v[156:157], v[184:185] op_sel_hi:[1,0,1]
	v_lshlrev_b32_e32 v160, 16, v136
	v_pk_add_f32 v[184:185], v[220:221], v[184:185] op_sel:[1,0] op_sel_hi:[0,1]
	v_mov_b32_e32 v220, v223
	v_mov_b32_e32 v221, v186
	v_pk_mul_f32 v[220:221], v[40:41], v[220:221]
	v_and_b32_e32 v156, 0xffff0000, v137
	v_pk_fma_f32 v[220:221], v[38:39], v[222:223], v[220:221]
	v_lshlrev_b32_e32 v162, 16, v158
	v_pk_fma_f32 v[186:187], v[10:11], v[186:187], v[220:221]
	v_and_b32_e32 v220, 0xffff0000, v136
	v_mov_b32_e32 v218, v220
	v_lshlrev_b32_e32 v221, 16, v137
	v_pk_mul_f32 v[136:137], v[20:21], v[218:219]
	v_pk_mul_f32 v[218:219], v[22:23], v[220:221]
	v_pk_fma_f32 v[136:137], v[24:25], v[160:161], v[136:137] op_sel_hi:[1,0,1]
	v_and_b32_e32 v160, 0xffff0000, v159
	v_pk_add_f32 v[136:137], v[218:219], v[136:137] op_sel:[1,0] op_sel_hi:[0,1]
	v_mov_b32_e32 v218, v221
	v_mov_b32_e32 v219, v156
	v_pk_mul_f32 v[218:219], v[28:29], v[218:219]
	v_and_b32_e32 v190, 0xffff0000, v189
	v_pk_fma_f32 v[218:219], v[26:27], v[220:221], v[218:219]
	v_and_b32_e32 v168, 0xffff0000, v167
	v_pk_fma_f32 v[156:157], v[22:23], v[156:157], v[218:219]
	v_and_b32_e32 v219, 0xffff0000, v158
	v_mov_b32_e32 v216, v219
	v_lshlrev_b32_e32 v218, 16, v159
	v_pk_mul_f32 v[158:159], v[14:15], v[216:217]
	v_pk_mul_f32 v[216:217], v[32:33], v[218:219]
	v_pk_fma_f32 v[158:159], v[30:31], v[162:163], v[158:159] op_sel_hi:[1,0,1]
	v_lshlrev_b32_e32 v162, 16, v188
	v_pk_fma_f32 v[158:159], v[16:17], v[218:219], v[158:159]
	v_mov_b32_e32 v219, v160
	v_pk_fma_f32 v[216:217], v[34:35], v[218:219], v[216:217] op_sel:[0,0,1] op_sel_hi:[1,1,0]
	v_and_b32_e32 v172, 0xffff0000, v171
	v_pk_fma_f32 v[160:161], v[16:17], v[160:161], v[216:217]
	v_and_b32_e32 v216, 0xffff0000, v188
	v_mov_b32_e32 v212, v216
	v_lshlrev_b32_e32 v217, 16, v189
	v_pk_mul_f32 v[188:189], v[8:9], v[212:213]
	v_pk_mul_f32 v[212:213], v[10:11], v[216:217]
	v_pk_fma_f32 v[188:189], v[36:37], v[162:163], v[188:189] op_sel_hi:[1,0,1]
	v_lshlrev_b32_e32 v162, 16, v166
	v_pk_add_f32 v[188:189], v[212:213], v[188:189] op_sel:[1,0] op_sel_hi:[0,1]
	v_mov_b32_e32 v212, v217
	v_mov_b32_e32 v213, v190
	v_pk_mul_f32 v[212:213], v[40:41], v[212:213]
	v_and_b32_e32 v194, 0xffff0000, v193
	v_pk_fma_f32 v[212:213], v[38:39], v[216:217], v[212:213]
	v_and_b32_e32 v176, 0xffff0000, v175
	v_pk_fma_f32 v[190:191], v[10:11], v[190:191], v[212:213]
	v_and_b32_e32 v212, 0xffff0000, v166
	v_mov_b32_e32 v206, v212
	v_lshlrev_b32_e32 v213, 16, v167
	v_pk_mul_f32 v[166:167], v[20:21], v[206:207]
	v_pk_mul_f32 v[206:207], v[22:23], v[212:213]
	v_pk_fma_f32 v[166:167], v[24:25], v[162:163], v[166:167] op_sel_hi:[1,0,1]
	v_lshlrev_b32_e32 v162, 16, v170
	v_pk_add_f32 v[166:167], v[206:207], v[166:167] op_sel:[1,0] op_sel_hi:[0,1]
	v_mov_b32_e32 v206, v213
	v_mov_b32_e32 v207, v168
	v_pk_mul_f32 v[206:207], v[28:29], v[206:207]
	v_and_b32_e32 v182, 0xffff0000, v179
	v_pk_fma_f32 v[206:207], v[26:27], v[212:213], v[206:207]
	v_mov_b32_e32 v210, v214
	v_pk_fma_f32 v[168:169], v[22:23], v[168:169], v[206:207]
	v_and_b32_e32 v207, 0xffff0000, v170
	v_mov_b32_e32 v204, v207
	v_lshlrev_b32_e32 v206, 16, v171
	v_pk_mul_f32 v[170:171], v[14:15], v[204:205]
	v_pk_mul_f32 v[204:205], v[32:33], v[206:207]
	v_pk_fma_f32 v[170:171], v[30:31], v[162:163], v[170:171] op_sel_hi:[1,0,1]
	v_lshlrev_b32_e32 v162, 16, v192
	v_pk_fma_f32 v[170:171], v[16:17], v[206:207], v[170:171]
	v_mov_b32_e32 v207, v172
	v_pk_fma_f32 v[204:205], v[34:35], v[206:207], v[204:205] op_sel:[0,0,1] op_sel_hi:[1,1,0]
	v_pk_add_f32 v[82:83], v[12:13], v[82:83]
	v_pk_fma_f32 v[172:173], v[16:17], v[172:173], v[204:205]
	v_and_b32_e32 v204, 0xffff0000, v192
	v_mov_b32_e32 v202, v204
	v_lshlrev_b32_e32 v205, 16, v193
	v_pk_mul_f32 v[192:193], v[8:9], v[202:203]
	v_pk_mul_f32 v[202:203], v[10:11], v[204:205]
	v_pk_fma_f32 v[192:193], v[36:37], v[162:163], v[192:193] op_sel_hi:[1,0,1]
	v_lshlrev_b32_e32 v162, 16, v174
	v_pk_add_f32 v[192:193], v[202:203], v[192:193] op_sel:[1,0] op_sel_hi:[0,1]
	v_mov_b32_e32 v202, v205
	v_mov_b32_e32 v203, v194
	v_pk_mul_f32 v[202:203], v[40:41], v[202:203]
	v_pk_add_f32 v[96:97], v[12:13], v[96:97]
	v_pk_fma_f32 v[202:203], v[38:39], v[204:205], v[202:203]
	v_pk_add_f32 v[184:185], v[6:7], v[184:185]
	v_pk_fma_f32 v[194:195], v[10:11], v[194:195], v[202:203]
	v_and_b32_e32 v202, 0xffff0000, v174
	v_mov_b32_e32 v200, v202
	v_lshlrev_b32_e32 v203, 16, v175
	v_pk_mul_f32 v[174:175], v[20:21], v[200:201]
	v_pk_mul_f32 v[200:201], v[22:23], v[202:203]
	v_pk_fma_f32 v[174:175], v[24:25], v[162:163], v[174:175] op_sel_hi:[1,0,1]
	v_lshlrev_b32_e32 v162, 16, v178
	v_pk_add_f32 v[174:175], v[200:201], v[174:175] op_sel:[1,0] op_sel_hi:[0,1]
	v_mov_b32_e32 v200, v203
	v_mov_b32_e32 v201, v176
	v_pk_mul_f32 v[200:201], v[28:29], v[200:201]
	v_pk_add_f32 v[186:187], v[6:7], v[186:187]
	v_pk_fma_f32 v[200:201], v[26:27], v[202:203], v[200:201]
	v_pk_add_f32 v[136:137], v[18:19], v[136:137]
	v_pk_fma_f32 v[176:177], v[22:23], v[176:177], v[200:201]
	v_and_b32_e32 v201, 0xffff0000, v178
	v_mov_b32_e32 v198, v201
	v_lshlrev_b32_e32 v200, 16, v179
	v_pk_mul_f32 v[178:179], v[14:15], v[198:199]
	v_pk_mul_f32 v[198:199], v[32:33], v[200:201]
	v_pk_fma_f32 v[178:179], v[30:31], v[162:163], v[178:179] op_sel_hi:[1,0,1]
	v_and_b32_e32 v162, 0xffff0000, v165
	v_pk_fma_f32 v[178:179], v[16:17], v[200:201], v[178:179]
	v_mov_b32_e32 v201, v182
	v_pk_fma_f32 v[198:199], v[34:35], v[200:201], v[198:199] op_sel:[0,0,1] op_sel_hi:[1,1,0]
	v_and_b32_e32 v200, 0xffff0000, v164
	v_mov_b32_e32 v196, v200
	v_pk_fma_f32 v[182:183], v[16:17], v[182:183], v[198:199]
	v_lshlrev_b32_e32 v198, 16, v164
	v_lshlrev_b32_e32 v201, 16, v165
	v_pk_mul_f32 v[164:165], v[8:9], v[196:197]
	v_pk_mul_f32 v[196:197], v[10:11], v[200:201]
	v_pk_fma_f32 v[164:165], v[36:37], v[198:199], v[164:165] op_sel_hi:[1,0,1]
	v_pk_add_f32 v[156:157], v[18:19], v[156:157]
	v_pk_add_f32 v[164:165], v[196:197], v[164:165] op_sel:[1,0] op_sel_hi:[0,1]
	v_pk_add_f32 v[196:197], v[6:7], v[164:165]
	v_mov_b32_e32 v164, v201
	v_mov_b32_e32 v165, v162
	v_pk_mul_f32 v[164:165], v[40:41], v[164:165]
	v_pk_add_f32 v[158:159], v[12:13], v[158:159]
	v_pk_fma_f32 v[164:165], v[38:39], v[200:201], v[164:165]
	v_pk_add_f32 v[160:161], v[12:13], v[160:161]
	v_pk_fma_f32 v[162:163], v[10:11], v[162:163], v[164:165]
	v_pk_mul_f32 v[164:165], v[22:23], v[214:215]
	v_pk_add_f32 v[198:199], v[6:7], v[162:163]
	v_pk_mul_f32 v[162:163], v[20:21], v[210:211]
	v_pk_add_f32 v[188:189], v[6:7], v[188:189]
	v_pk_fma_f32 v[162:163], v[24:25], v[226:227], v[162:163] op_sel_hi:[1,0,1]
	v_pk_add_f32 v[190:191], v[6:7], v[190:191]
	v_pk_add_f32 v[162:163], v[164:165], v[162:163] op_sel:[1,0] op_sel_hi:[0,1]
	v_mov_b32_e32 v164, v215
	v_mov_b32_e32 v165, v208
	v_pk_mul_f32 v[164:165], v[28:29], v[164:165]
	v_pk_add_f32 v[166:167], v[18:19], v[166:167]
	v_pk_fma_f32 v[164:165], v[26:27], v[214:215], v[164:165]
	v_pk_add_f32 v[168:169], v[18:19], v[168:169]
	v_pk_fma_f32 v[164:165], v[22:23], v[208:209], v[164:165]
	v_pk_add_f32 v[170:171], v[12:13], v[170:171]
	v_pk_add_f32 v[172:173], v[12:13], v[172:173]
	v_pk_add_f32 v[192:193], v[6:7], v[192:193]
	v_pk_add_f32 v[194:195], v[6:7], v[194:195]
	v_pk_add_f32 v[174:175], v[18:19], v[174:175]
	v_pk_add_f32 v[176:177], v[18:19], v[176:177]
	v_pk_add_f32 v[178:179], v[12:13], v[178:179]
	v_pk_add_f32 v[182:183], v[12:13], v[182:183]
	v_pk_add_f32 v[162:163], v[18:19], v[162:163]
	v_pk_add_f32 v[164:165], v[18:19], v[164:165]

.LBB0_380:
	s_or_b64 exec, exec, s[2:3]
	s_waitcnt lgkmcnt(0)
	s_barrier
	ds_read2_b64 v[200:203], v235 offset1:1
	s_movk_i32 s2, 0x2000
	s_waitcnt lgkmcnt(0)
	v_mov_b32_e32 v205, v200
	v_mov_b32_e32 v200, v203
	v_mov_b32_e32 v204, v202
	v_pk_fma_f32 v[192:193], v[4:5], v[192:193], v[200:201]
	ds_read2_b64 v[200:203], v236 offset1:1
	v_pk_fma_f32 v[196:197], v[4:5], v[196:197], v[204:205]
	v_pk_mul_f32 v[192:193], v[166:167], v[192:193]
	v_pk_mul_f32 v[196:197], v[174:175], v[196:197]
	s_waitcnt lgkmcnt(0)
	v_mov_b32_e32 v205, v202
	v_mov_b32_e32 v202, v201
	v_mov_b32_e32 v204, v200
	v_pk_fma_f32 v[194:195], v[4:5], v[194:195], v[202:203]
	ds_read2_b64 v[200:203], v234 offset1:1
	v_pk_fma_f32 v[198:199], v[4:5], v[198:199], v[204:205]
	v_pk_mul_f32 v[194:195], v[168:169], v[194:195]
	v_pk_mul_f32 v[198:199], v[176:177], v[198:199]
	s_waitcnt lgkmcnt(0)
	v_mov_b32_e32 v205, v200
	v_mov_b32_e32 v200, v203
	v_mov_b32_e32 v204, v202
	v_pk_fma_f32 v[184:185], v[4:5], v[184:185], v[200:201]
	ds_read2_b64 v[200:203], v233 offset1:1
	v_pk_fma_f32 v[188:189], v[4:5], v[188:189], v[204:205]
	s_waitcnt lgkmcnt(0)
	s_barrier
	v_mov_b32_e32 v204, v201
	v_mov_b32_e32 v205, v203
	v_mov_b32_e32 v201, v202
	v_lshl_add_u64 v[202:203], s[76:77], 1, v[110:111]
	v_pk_fma_f32 v[186:187], v[4:5], v[186:187], v[204:205]
	v_add_co_u32_e32 v204, vcc, s2, v202
	v_pk_fma_f32 v[190:191], v[4:5], v[190:191], v[200:201]
	s_nop 0
	v_addc_co_u32_e32 v205, vcc, 0, v203, vcc
	v_cvt_pk_bf16_f32 v200, v197, v196
	v_cvt_pk_bf16_f32 v201, v198, v199
	global_store_dwordx2 v[202:203], v[200:201], off
	v_add_co_u32_e32 v202, vcc, 0x3000, v202
	v_cvt_pk_bf16_f32 v200, v193, v192
	v_cvt_pk_bf16_f32 v201, v194, v195
	v_pk_mul_f32 v[188:189], v[136:137], v[188:189]
	s_nop 0
	v_addc_co_u32_e32 v203, vcc, 0, v203, vcc
	v_pk_mul_f32 v[184:185], v[162:163], v[184:185]
	v_pk_mul_f32 v[186:187], v[164:165], v[186:187]
	v_pk_mul_f32 v[190:191], v[156:157], v[190:191]
	global_store_dwordx2 v[204:205], v[200:201], off offset:-4096
	v_cvt_pk_bf16_f32 v200, v189, v188
	v_cvt_pk_bf16_f32 v201, v190, v191
	s_andn2_b64 vcc, exec, s[74:75]
	global_store_dwordx2 v[204:205], v[200:201], off
	v_cvt_pk_bf16_f32 v200, v185, v184
	v_cvt_pk_bf16_f32 v201, v186, v187
	global_store_dwordx2 v[202:203], v[200:201], off
	s_cbranch_vccnz .LBB0_355
	global_load_dwordx2 v[164:165], v[112:113], off
	v_mov_b32_e32 v163, 0
	v_mov_b32_e32 v197, 0
	s_and_saveexec_b64 s[2:3], s[4:5]
	s_cbranch_execz .LBB0_383
	global_load_ushort v197, v[112:113], off offset:-2
.LBB0_383:
	s_or_b64 exec, exec, s[2:3]
	s_and_saveexec_b64 s[2:3], s[6:7]
	s_cbranch_execz .LBB0_385
	global_load_ushort v163, v[112:113], off offset:8
.LBB0_385:
	s_or_b64 exec, exec, s[2:3]
	global_load_dwordx2 v[178:179], v[114:115], off
	v_mov_b32_e32 v183, 0
	v_mov_b32_e32 v199, 0
	s_and_saveexec_b64 s[2:3], s[4:5]
	s_cbranch_execz .LBB0_387
	global_load_ushort v199, v[114:115], off offset:-2
.LBB0_387:
	s_or_b64 exec, exec, s[2:3]
	s_and_saveexec_b64 s[2:3], s[6:7]
	s_cbranch_execz .LBB0_389
	global_load_ushort v183, v[114:115], off offset:8
.LBB0_389:
	s_or_b64 exec, exec, s[2:3]
	global_load_dwordx2 v[174:175], v[116:117], off
	v_mov_b32_e32 v177, 0
	v_mov_b32_e32 v201, 0
	s_and_saveexec_b64 s[2:3], s[4:5]
	s_cbranch_execz .LBB0_391
	global_load_ushort v201, v[116:117], off offset:-2
.LBB0_391:
	s_or_b64 exec, exec, s[2:3]
	s_and_saveexec_b64 s[2:3], s[6:7]
	s_cbranch_execz .LBB0_393
	global_load_ushort v177, v[116:117], off offset:8
.LBB0_393:
	s_or_b64 exec, exec, s[2:3]
	global_load_dwordx2 v[192:193], v[118:119], off
	v_mov_b32_e32 v195, 0
	v_mov_b32_e32 v203, 0
	s_and_saveexec_b64 s[2:3], s[4:5]
	s_cbranch_execz .LBB0_395
	global_load_ushort v203, v[118:119], off offset:-2
.LBB0_395:
	s_or_b64 exec, exec, s[2:3]
	s_and_saveexec_b64 s[2:3], s[6:7]
	s_cbranch_execz .LBB0_397
	global_load_ushort v195, v[118:119], off offset:8
.LBB0_397:
	s_or_b64 exec, exec, s[2:3]
	global_load_dwordx2 v[170:171], v[120:121], off
	v_mov_b32_e32 v173, 0
	v_mov_b32_e32 v205, 0
	s_and_saveexec_b64 s[2:3], s[4:5]
	s_cbranch_execz .LBB0_399
	global_load_ushort v205, v[120:121], off offset:-2
.LBB0_399:
	s_or_b64 exec, exec, s[2:3]
	s_and_saveexec_b64 s[2:3], s[6:7]
	s_cbranch_execz .LBB0_401
	global_load_ushort v173, v[120:121], off offset:8
.LBB0_401:
	s_or_b64 exec, exec, s[2:3]
	global_load_dwordx2 v[166:167], v[122:123], off
	v_mov_b32_e32 v169, 0
	v_mov_b32_e32 v207, 0
	s_and_saveexec_b64 s[2:3], s[4:5]
	s_cbranch_execz .LBB0_403
	global_load_ushort v207, v[122:123], off offset:-2
.LBB0_403:
	s_or_b64 exec, exec, s[2:3]
	s_and_saveexec_b64 s[2:3], s[6:7]
	s_cbranch_execz .LBB0_405
	global_load_ushort v169, v[122:123], off offset:8
.LBB0_405:
	s_or_b64 exec, exec, s[2:3]
	global_load_dwordx2 v[188:189], v[124:125], off
	v_mov_b32_e32 v191, 0
	v_mov_b32_e32 v213, 0
	s_and_saveexec_b64 s[2:3], s[4:5]
	s_cbranch_execz .LBB0_407
	global_load_ushort v213, v[124:125], off offset:-2
.LBB0_407:
	s_or_b64 exec, exec, s[2:3]
	s_and_saveexec_b64 s[2:3], s[6:7]
	s_cbranch_execz .LBB0_409
	global_load_ushort v191, v[124:125], off offset:8
.LBB0_409:
	s_or_b64 exec, exec, s[2:3]
	global_load_dwordx2 v[158:159], v[126:127], off
	v_mov_b32_e32 v161, 0
	v_mov_b32_e32 v217, 0
	s_and_saveexec_b64 s[2:3], s[4:5]
	s_cbranch_execz .LBB0_411
	global_load_ushort v217, v[126:127], off offset:-2
.LBB0_411:
	s_or_b64 exec, exec, s[2:3]
	s_and_saveexec_b64 s[2:3], s[6:7]
	s_cbranch_execz .LBB0_413
	global_load_ushort v161, v[126:127], off offset:8
.LBB0_413:
	s_or_b64 exec, exec, s[2:3]
	global_load_dwordx2 v[136:137], v[128:129], off
	v_mov_b32_e32 v157, 0
	v_mov_b32_e32 v219, 0
	s_and_saveexec_b64 s[2:3], s[4:5]
	s_cbranch_execz .LBB0_415
	global_load_ushort v219, v[128:129], off offset:-2
.LBB0_415:
	s_or_b64 exec, exec, s[2:3]
	s_and_saveexec_b64 s[2:3], s[6:7]
	s_cbranch_execz .LBB0_417
	global_load_ushort v157, v[128:129], off offset:8
.LBB0_417:
	s_or_b64 exec, exec, s[2:3]
	global_load_dwordx2 v[184:185], v[130:131], off
	v_mov_b32_e32 v187, 0
	v_mov_b32_e32 v221, 0
	s_and_saveexec_b64 s[2:3], s[4:5]
	s_cbranch_execz .LBB0_419
	global_load_ushort v221, v[130:131], off offset:-2
.LBB0_419:
	s_or_b64 exec, exec, s[2:3]
	s_and_saveexec_b64 s[2:3], s[6:7]
	s_cbranch_execz .LBB0_421
	global_load_ushort v187, v[130:131], off offset:8
.LBB0_421:
	s_or_b64 exec, exec, s[2:3]
	global_load_dwordx2 v[82:83], v[132:133], off
	v_mov_b32_e32 v97, 0
	v_mov_b32_e32 v223, 0
	s_and_saveexec_b64 s[2:3], s[4:5]
	s_cbranch_execz .LBB0_423
	global_load_ushort v223, v[132:133], off offset:-2
.LBB0_423:
	s_or_b64 exec, exec, s[2:3]
	s_and_saveexec_b64 s[2:3], s[6:7]
	s_cbranch_execz .LBB0_425
	global_load_ushort v97, v[132:133], off offset:8
.LBB0_425:
	s_or_b64 exec, exec, s[2:3]
	global_load_dwordx2 v[224:225], v[134:135], off
	v_mov_b32_e32 v209, 0
	v_mov_b32_e32 v211, 0
	s_and_saveexec_b64 s[2:3], s[4:5]
	s_cbranch_execz .LBB0_427
	global_load_ushort v211, v[134:135], off offset:-2
.LBB0_427:
	s_or_b64 exec, exec, s[2:3]
	s_and_saveexec_b64 s[2:3], s[6:7]
	s_cbranch_execz .LBB0_354
	global_load_ushort v209, v[134:135], off offset:8
	s_branch .LBB0_354

.LBB0_432:
	s_ashr_i32 s61, s60, 31
	v_readlane_b32 s36, v254, 43
	s_lshl_b64 s[2:3], s[60:61], 2
	v_readlane_b32 s50, v254, 57
	v_readlane_b32 s51, v254, 58
	s_add_u32 s4, s50, s2
	v_readlane_b32 s40, v254, 47
	v_readlane_b32 s41, v254, 48
	v_readlane_b32 s42, v254, 49
	v_readlane_b32 s43, v254, 50
	v_readlane_b32 s44, v254, 51
	v_readlane_b32 s45, v254, 52
	v_readlane_b32 s46, v254, 53
	v_readlane_b32 s47, v254, 54
	v_readlane_b32 s48, v254, 55
	v_readlane_b32 s49, v254, 56
	s_addc_u32 s5, s51, s3
	v_readlane_b32 s37, v254, 44
	s_add_u32 s36, s36, s2
	v_readlane_b32 s40, v254, 9
	s_addc_u32 s37, s37, s3
	v_readlane_b32 s54, v254, 23
	v_mov_b32_e32 v44, v180
	v_readlane_b32 s55, v254, 24
	s_add_u32 s2, s54, s2
	s_addc_u32 s3, s55, s3
	global_load_dword v22, v9, s[4:5]
	global_load_dword v98, v9, s[36:37]
	global_load_dword v101, v9, s[2:3]
	global_load_dword v11, v158, s[4:5]
	global_load_dword v102, v159, s[2:3]
	global_load_dword v100, v160, s[2:3]
	global_load_dword v27, v158, s[36:37]
	global_load_dword v42, v161, s[2:3]
	global_load_dword v38, v162, s[2:3]
	global_load_dword v182, v158, s[2:3]
	global_load_dword v177, v163, s[36:37]
	global_load_dword v16, v163, s[2:3]
	global_load_dword v14, v164, s[2:3]
	global_load_dword v15, v165, s[2:3]
	global_load_dword v10, v166, s[4:5]
	global_load_dword v93, v166, s[36:37]
	global_load_dword v94, v166, s[2:3]
	global_load_dword v23, v167, s[4:5]
	global_load_dword v96, v168, s[2:3]
	global_load_dword v95, v169, s[2:3]
	global_load_dword v183, v167, s[36:37]
	global_load_dword v186, v170, s[2:3]
	global_load_dword v184, v171, s[2:3]
	global_load_dword v185, v167, s[2:3]
	global_load_dword v17, v172, s[36:37]
	global_load_dword v26, v172, s[2:3]
	global_load_dword v24, v173, s[2:3]
	global_load_dword v25, v174, s[2:3]
	v_ashrrev_i32_e32 v45, 31, v44
	v_lshrrev_b32_e32 v0, 26, v45
	v_add_u32_e32 v0, v44, v0
	v_ashrrev_i32_e32 v132, 6, v0
	v_and_b32_e32 v0, 0xffffffc0, v0
	v_sub_u32_e32 v88, v44, v0
	v_lshlrev_b32_e32 v18, 2, v88
	v_lshlrev_b32_e32 v4, 1, v132
	v_ashrrev_i32_e32 v19, 31, v18
	v_ashrrev_i32_e32 v5, 31, v4
	v_lshl_add_u64 v[2:3], v[18:19], 1, s[20:21]
	v_lshlrev_b64 v[12:13], 9, v[4:5]
	v_lshl_add_u64 v[0:1], v[2:3], 0, v[12:13]
	v_mad_i64_i32 v[6:7], s[2:3], s60, v164, v[0:1]
	global_load_dwordx2 v[46:47], v[6:7], off
	v_cmp_lt_i32_e32 vcc, 0, v88
	v_mov_b32_e32 v92, v9
	v_readlane_b32 s38, v254, 45
	v_readlane_b32 s39, v254, 46
	v_readlane_b32 s41, v254, 10
	v_readlane_b32 s42, v254, 11
	v_readlane_b32 s43, v254, 12
	v_readlane_b32 s44, v254, 13
	v_readlane_b32 s45, v254, 14
	v_readlane_b32 s46, v254, 15
	v_readlane_b32 s47, v254, 16
	v_readlane_b32 s48, v254, 17
	v_readlane_b32 s49, v254, 18
	v_readlane_b32 s50, v254, 19
	v_readlane_b32 s51, v254, 20
	v_readlane_b32 s52, v254, 21
	v_readlane_b32 s53, v254, 22
	s_and_saveexec_b64 s[2:3], vcc
	s_cbranch_execz .LBB0_434
	global_load_ushort v92, v[6:7], off offset:-2
.LBB0_434:
	s_or_b64 exec, exec, s[2:3]
	v_cmp_ne_u32_e64 s[4:5], 63, v88
	v_mov_b32_e32 v187, 0
	v_mov_b32_e32 v103, 0
	s_and_saveexec_b64 s[2:3], s[4:5]
	s_cbranch_execz .LBB0_436
	global_load_ushort v103, v[6:7], off offset:8
.LBB0_436:
	s_or_b64 exec, exec, s[2:3]
	s_add_i32 s9, s60, 0x800
	v_mad_i64_i32 v[6:7], s[2:3], s9, v164, v[0:1]
	global_load_dwordx2 v[68:69], v[6:7], off
	s_and_saveexec_b64 s[2:3], vcc
	s_cbranch_execz .LBB0_438
	global_load_ushort v187, v[6:7], off offset:-2
.LBB0_438:
	s_or_b64 exec, exec, s[2:3]
	v_mov_b32_e32 v178, 0
	v_mov_b32_e32 v188, 0
	s_and_saveexec_b64 s[2:3], s[4:5]
	s_cbranch_execz .LBB0_440
	global_load_ushort v188, v[6:7], off offset:8
.LBB0_440:
	s_or_b64 exec, exec, s[2:3]
	s_add_i32 s7, s60, 0x1000
	v_mad_i64_i32 v[6:7], s[2:3], s7, v164, v[0:1]
	global_load_dwordx2 v[28:29], v[6:7], off
	s_and_saveexec_b64 s[2:3], vcc
	s_cbranch_execz .LBB0_442
	global_load_ushort v178, v[6:7], off offset:-2
.LBB0_442:
	s_or_b64 exec, exec, s[2:3]
	v_mov_b32_e32 v97, 0
	v_mov_b32_e32 v31, 0
	s_and_saveexec_b64 s[2:3], s[4:5]
	s_cbranch_execz .LBB0_444
	global_load_ushort v31, v[6:7], off offset:8
.LBB0_444:
	s_or_b64 exec, exec, s[2:3]
	v_or_b32_e32 v4, 1, v4
	v_ashrrev_i32_e32 v5, 31, v4
	v_lshlrev_b64 v[20:21], 9, v[4:5]
	s_mul_hi_i32 s63, s60, 0xa000
	s_mul_i32 s62, s60, 0xa000
	v_lshl_add_u64 v[2:3], v[2:3], 0, v[20:21]
	v_lshl_add_u64 v[4:5], v[2:3], 0, s[62:63]
	global_load_dwordx2 v[48:49], v[4:5], off
	s_and_saveexec_b64 s[2:3], vcc
	s_cbranch_execz .LBB0_446
	global_load_ushort v97, v[4:5], off offset:-2
.LBB0_446:
	s_or_b64 exec, exec, s[2:3]
	v_mov_b32_e32 v189, 0
	v_mov_b32_e32 v99, 0
	s_and_saveexec_b64 s[2:3], s[4:5]
	s_cbranch_execz .LBB0_448
	global_load_ushort v99, v[4:5], off offset:8
.LBB0_448:
	s_or_b64 exec, exec, s[2:3]
	s_mul_hi_i32 s3, s9, 0xa000
	s_mul_i32 s2, s9, 0xa000
	v_lshl_add_u64 v[4:5], v[2:3], 0, s[2:3]
	global_load_dwordx2 v[78:79], v[4:5], off
	s_and_saveexec_b64 s[2:3], vcc
	s_cbranch_execz .LBB0_450
	global_load_ushort v189, v[4:5], off offset:-2
.LBB0_450:
	s_or_b64 exec, exec, s[2:3]
	v_mov_b32_e32 v179, 0
	v_mov_b32_e32 v190, 0
	s_and_saveexec_b64 s[2:3], s[4:5]
	s_cbranch_execz .LBB0_452
	global_load_ushort v190, v[4:5], off offset:8
.LBB0_452:
	s_or_b64 exec, exec, s[2:3]
	s_mul_hi_i32 s3, s7, 0xa000
	s_mul_i32 s2, s7, 0xa000
	v_lshl_add_u64 v[4:5], v[2:3], 0, s[2:3]
	global_load_dwordx2 v[32:33], v[4:5], off
	s_and_saveexec_b64 s[2:3], vcc
	s_cbranch_execz .LBB0_454
	global_load_ushort v179, v[4:5], off offset:-2
.LBB0_454:
	s_or_b64 exec, exec, s[2:3]
	v_mov_b32_e32 v90, 0
	v_mov_b32_e32 v35, 0
	s_and_saveexec_b64 s[2:3], s[4:5]
	s_cbranch_execz .LBB0_456
	global_load_ushort v35, v[4:5], off offset:8
.LBB0_456:
	s_or_b64 exec, exec, s[2:3]
	s_add_i32 s11, s60, 0x400
	v_mad_i64_i32 v[4:5], s[2:3], s11, v164, v[0:1]
	global_load_dwordx2 v[50:51], v[4:5], off
	s_and_saveexec_b64 s[2:3], vcc
	s_cbranch_execz .LBB0_458
	global_load_ushort v90, v[4:5], off offset:-2
.LBB0_458:
	s_or_b64 exec, exec, s[2:3]
	v_mov_b32_e32 v191, 0
	v_mov_b32_e32 v104, 0
	s_and_saveexec_b64 s[2:3], s[4:5]
	s_cbranch_execz .LBB0_460
	global_load_ushort v104, v[4:5], off offset:8
.LBB0_460:
	s_or_b64 exec, exec, s[2:3]
	s_add_i32 s9, s60, 0xc00
	v_mad_i64_i32 v[4:5], s[2:3], s9, v164, v[0:1]
	global_load_dwordx2 v[80:81], v[4:5], off
	s_and_saveexec_b64 s[2:3], vcc
	s_cbranch_execz .LBB0_462
	global_load_ushort v191, v[4:5], off offset:-2
.LBB0_462:
	s_or_b64 exec, exec, s[2:3]
	v_mov_b32_e32 v30, 0
	v_mov_b32_e32 v192, 0
	s_and_saveexec_b64 s[2:3], s[4:5]
	s_cbranch_execz .LBB0_464
	global_load_ushort v192, v[4:5], off offset:8
.LBB0_464:
	s_or_b64 exec, exec, s[2:3]
	s_add_i32 s7, s60, 0x1400
	v_mad_i64_i32 v[0:1], s[2:3], s7, v164, v[0:1]
	global_load_dwordx2 v[36:37], v[0:1], off
	s_and_saveexec_b64 s[2:3], vcc
	s_cbranch_execz .LBB0_466
	global_load_ushort v30, v[0:1], off offset:-2
.LBB0_466:
	s_or_b64 exec, exec, s[2:3]
	v_mov_b32_e32 v89, 0
	v_mov_b32_e32 v39, 0
	s_and_saveexec_b64 s[2:3], s[4:5]
	s_cbranch_execz .LBB0_468
	global_load_ushort v39, v[0:1], off offset:8
.LBB0_468:
	s_or_b64 exec, exec, s[2:3]
	s_mul_hi_i32 s65, s11, 0xa000
	s_mul_i32 s64, s11, 0xa000
	v_lshl_add_u64 v[0:1], v[2:3], 0, s[64:65]
	global_load_dwordx2 v[52:53], v[0:1], off
	s_and_saveexec_b64 s[2:3], vcc
	s_cbranch_execz .LBB0_470
	global_load_ushort v89, v[0:1], off offset:-2
.LBB0_470:
	s_or_b64 exec, exec, s[2:3]
	v_mov_b32_e32 v193, 0
	v_mov_b32_e32 v105, 0
	s_and_saveexec_b64 s[2:3], s[4:5]
	s_cbranch_execz .LBB0_472
	global_load_ushort v105, v[0:1], off offset:8
.LBB0_472:
	s_or_b64 exec, exec, s[2:3]
	s_mul_hi_i32 s3, s9, 0xa000
	s_mul_i32 s2, s9, 0xa000
	v_lshl_add_u64 v[0:1], v[2:3], 0, s[2:3]
	global_load_dwordx2 v[82:83], v[0:1], off
	s_and_saveexec_b64 s[2:3], vcc
	s_cbranch_execz .LBB0_474
	global_load_ushort v193, v[0:1], off offset:-2
.LBB0_474:
	s_or_b64 exec, exec, s[2:3]
	v_mov_b32_e32 v34, 0
	v_mov_b32_e32 v194, 0
	s_and_saveexec_b64 s[2:3], s[4:5]
	s_cbranch_execz .LBB0_476
	global_load_ushort v194, v[0:1], off offset:8
.LBB0_476:
	s_or_b64 exec, exec, s[2:3]
	s_mul_hi_i32 s3, s7, 0xa000
	s_mul_i32 s2, s7, 0xa000
	v_lshl_add_u64 v[0:1], v[2:3], 0, s[2:3]
	s_waitcnt vmcnt(0)
	v_lshlrev_b32_e32 v92, 16, v92
	v_lshlrev_b32_e32 v103, 16, v103
	v_lshlrev_b32_e32 v187, 16, v187
	v_lshlrev_b32_e32 v188, 16, v188
	v_lshlrev_b32_e32 v178, 16, v178
	v_lshlrev_b32_e32 v31, 16, v31
	v_lshlrev_b32_e32 v97, 16, v97
	v_lshlrev_b32_e32 v99, 16, v99
	v_lshlrev_b32_e32 v189, 16, v189
	v_lshlrev_b32_e32 v190, 16, v190
	v_lshlrev_b32_e32 v179, 16, v179
	v_lshlrev_b32_e32 v35, 16, v35
	v_lshlrev_b32_e32 v90, 16, v90
	v_lshlrev_b32_e32 v104, 16, v104
	v_lshlrev_b32_e32 v191, 16, v191
	v_lshlrev_b32_e32 v192, 16, v192
	v_lshlrev_b32_e32 v30, 16, v30
	v_lshlrev_b32_e32 v39, 16, v39
	v_lshlrev_b32_e32 v89, 16, v89
	v_lshlrev_b32_e32 v105, 16, v105
	v_lshlrev_b32_e32 v193, 16, v193
	v_lshlrev_b32_e32 v194, 16, v194
	global_load_dwordx2 v[40:41], v[0:1], off
	s_and_saveexec_b64 s[2:3], vcc
	s_cbranch_execz .LBB0_479
	global_load_ushort v2, v[0:1], off offset:-2
	s_waitcnt vmcnt(0)
	v_lshlrev_b32_e32 v34, 16, v2
	s_or_b64 exec, exec, s[2:3]
	v_mov_b32_e32 v43, 0
	s_and_saveexec_b64 s[2:3], s[4:5]
	s_cbranch_execnz .LBB0_480

.Lcoldzero_1:
	v_mov_b32_e32 v122, v123
	v_mov_b32_e32 v121, v123
	v_mov_b32_e32 v120, v123
	v_mov_b32_e32 v119, v123
	v_mov_b32_e32 v118, v123
	v_mov_b32_e32 v117, v123
	v_mov_b32_e32 v116, v123
	v_mov_b32_e32 v111, v123
	v_mov_b32_e32 v110, v123
	v_mov_b32_e32 v109, v123
	v_mov_b32_e32 v108, v123
	v_mov_b32_e32 v103, v123
	v_mov_b32_e32 v102, v123
	v_mov_b32_e32 v101, v123
	v_mov_b32_e32 v100, v123
	v_mov_b32_e32 v95, v123
	v_mov_b32_e32 v94, v123
	v_mov_b32_e32 v93, v123
	v_mov_b32_e32 v92, v123
	v_mov_b32_e32 v87, v123
	v_mov_b32_e32 v86, v123
	v_mov_b32_e32 v85, v123
	v_mov_b32_e32 v84, v123
	v_mov_b32_e32 v79, v123
	v_mov_b32_e32 v78, v123
	v_mov_b32_e32 v77, v123
	v_mov_b32_e32 v76, v123
	v_mov_b32_e32 v71, v123
	v_mov_b32_e32 v70, v123
	v_mov_b32_e32 v69, v123
	v_mov_b32_e32 v68, v123
	v_mov_b32_e32 v127, v123
	v_mov_b32_e32 v126, v123
	v_mov_b32_e32 v125, v123
	v_mov_b32_e32 v124, v123
	v_mov_b32_e32 v115, v123
	v_mov_b32_e32 v114, v123
	v_mov_b32_e32 v113, v123
	v_mov_b32_e32 v112, v123
	v_mov_b32_e32 v107, v123
	v_mov_b32_e32 v106, v123
	v_mov_b32_e32 v105, v123
	v_mov_b32_e32 v104, v123
	v_mov_b32_e32 v99, v123
	v_mov_b32_e32 v98, v123
	v_mov_b32_e32 v97, v123
	v_mov_b32_e32 v96, v123
	v_mov_b32_e32 v91, v123
	v_mov_b32_e32 v90, v123
	v_mov_b32_e32 v89, v123
	v_mov_b32_e32 v88, v123
	v_mov_b32_e32 v83, v123
	v_mov_b32_e32 v82, v123
	v_mov_b32_e32 v81, v123
	v_mov_b32_e32 v80, v123
	v_mov_b32_e32 v75, v123
	v_mov_b32_e32 v74, v123
	v_mov_b32_e32 v73, v123
	v_mov_b32_e32 v72, v123
	v_mov_b32_e32 v67, v123
	v_mov_b32_e32 v66, v123
	v_mov_b32_e32 v65, v123
	v_mov_b32_e32 v64, v123
	v_mov_b32_e32 v63, v123
	v_mov_b32_e32 v62, v123
	v_mov_b32_e32 v61, v123
	v_mov_b32_e32 v60, v123
	v_mov_b32_e32 v55, v123
	v_mov_b32_e32 v54, v123
	v_mov_b32_e32 v53, v123
	v_mov_b32_e32 v52, v123
	v_mov_b32_e32 v47, v123
	v_mov_b32_e32 v46, v123
	v_mov_b32_e32 v45, v123
	v_mov_b32_e32 v44, v123
	v_mov_b32_e32 v39, v123
	v_mov_b32_e32 v38, v123
	v_mov_b32_e32 v37, v123
	v_mov_b32_e32 v36, v123
	v_mov_b32_e32 v31, v123
	v_mov_b32_e32 v30, v123
	v_mov_b32_e32 v29, v123
	v_mov_b32_e32 v28, v123
	v_mov_b32_e32 v23, v123
	v_mov_b32_e32 v22, v123
	v_mov_b32_e32 v21, v123
	v_mov_b32_e32 v20, v123
	v_mov_b32_e32 v15, v123
	v_mov_b32_e32 v14, v123
	v_mov_b32_e32 v13, v123
	v_mov_b32_e32 v12, v123
	v_mov_b32_e32 v7, v123
	v_mov_b32_e32 v6, v123
	v_mov_b32_e32 v5, v123
	v_mov_b32_e32 v4, v123
	v_mov_b32_e32 v59, v123
	v_mov_b32_e32 v58, v123
	v_mov_b32_e32 v57, v123
	v_mov_b32_e32 v56, v123
	v_mov_b32_e32 v51, v123
	v_mov_b32_e32 v50, v123
	v_mov_b32_e32 v49, v123
	v_mov_b32_e32 v48, v123
	v_mov_b32_e32 v43, v123
	v_mov_b32_e32 v42, v123
	v_mov_b32_e32 v41, v123
	v_mov_b32_e32 v40, v123
	v_mov_b32_e32 v35, v123
	v_mov_b32_e32 v34, v123
	v_mov_b32_e32 v33, v123
	v_mov_b32_e32 v32, v123
	v_mov_b32_e32 v27, v123
	v_mov_b32_e32 v26, v123
	v_mov_b32_e32 v25, v123
	v_mov_b32_e32 v24, v123
	v_mov_b32_e32 v19, v123
	v_mov_b32_e32 v18, v123
	v_mov_b32_e32 v17, v123
	v_mov_b32_e32 v16, v123
	v_mov_b32_e32 v11, v123
	v_mov_b32_e32 v10, v123
	v_mov_b32_e32 v9, v123
	v_mov_b32_e32 v8, v123
	v_mov_b32_e32 v3, v123
	v_mov_b32_e32 v2, v123
	v_mov_b32_e32 v1, v123
	v_mov_b32_e32 v0, v123
	s_branch .LBB0_879

.LBB0_876:
	v_readlane_b32 s4, v255, 50
	v_readlane_b32 s5, v255, 51
	s_add_u32 s6, s4, s60
	s_addc_u32 s7, s5, s61
	s_and_b64 s[4:5], s[12:13], exec
	v_readlane_b32 s4, v255, 6
	s_cselect_b32 s65, s7, s17
	s_cselect_b32 s64, s6, s16
	v_readlane_b32 s5, v255, 7
	s_add_u32 s6, s4, s62
	s_addc_u32 s7, s5, s63
	s_and_b64 s[4:5], s[12:13], exec
	v_mov_b32_e32 v123, 0
	s_cselect_b32 s67, s7, s37
	s_cselect_b32 s66, s6, s36
	s_and_b64 vcc, exec, s[10:11]
	s_cbranch_vccnz .Lcoldzero_1
	v_mov_b64_e32 v[0:1], 0
	s_mov_b32 s4, 0
	s_mov_b64 s[54:55], 0
	v_mov_b64_e32 v[2:3], 0
	v_mov_b64_e32 v[4:5], 0
	v_mov_b64_e32 v[6:7], 0
	v_mov_b64_e32 v[8:9], 0
	v_mov_b64_e32 v[10:11], 0
	v_mov_b64_e32 v[12:13], 0
	v_mov_b64_e32 v[14:15], 0
	v_mov_b64_e32 v[16:17], 0
	v_mov_b64_e32 v[18:19], 0
	v_mov_b64_e32 v[20:21], 0
	v_mov_b64_e32 v[22:23], 0
	v_mov_b64_e32 v[24:25], 0
	v_mov_b64_e32 v[26:27], 0
	v_mov_b64_e32 v[28:29], 0
	v_mov_b64_e32 v[30:31], 0
	v_mov_b64_e32 v[32:33], 0
	v_mov_b64_e32 v[34:35], 0
	v_mov_b64_e32 v[36:37], 0
	v_mov_b64_e32 v[38:39], 0
	v_mov_b64_e32 v[40:41], 0
	v_mov_b64_e32 v[42:43], 0
	v_mov_b64_e32 v[44:45], 0
	v_mov_b64_e32 v[46:47], 0
	v_mov_b64_e32 v[48:49], 0
	v_mov_b64_e32 v[50:51], 0
	v_mov_b64_e32 v[52:53], 0
	v_mov_b64_e32 v[54:55], 0
	v_mov_b64_e32 v[56:57], 0
	v_mov_b64_e32 v[58:59], 0
	v_mov_b64_e32 v[60:61], 0
	v_mov_b64_e32 v[62:63], 0
	v_mov_b64_e32 v[64:65], 0
	v_mov_b64_e32 v[66:67], 0
	v_mov_b64_e32 v[68:69], 0
	v_mov_b64_e32 v[70:71], 0
	v_mov_b64_e32 v[72:73], 0
	v_mov_b64_e32 v[74:75], 0
	v_mov_b64_e32 v[76:77], 0
	v_mov_b64_e32 v[78:79], 0
	v_mov_b64_e32 v[80:81], 0
	v_mov_b64_e32 v[82:83], 0
	v_mov_b64_e32 v[84:85], 0
	v_mov_b64_e32 v[86:87], 0
	v_mov_b64_e32 v[88:89], 0
	v_mov_b64_e32 v[90:91], 0
	v_mov_b64_e32 v[92:93], 0
	v_mov_b64_e32 v[94:95], 0
	v_mov_b64_e32 v[96:97], 0
	v_mov_b64_e32 v[98:99], 0
	v_mov_b64_e32 v[100:101], 0
	v_mov_b64_e32 v[102:103], 0
	v_mov_b64_e32 v[104:105], 0
	v_mov_b64_e32 v[106:107], 0
	v_mov_b64_e32 v[108:109], 0
	v_mov_b64_e32 v[110:111], 0
	v_mov_b64_e32 v[112:113], 0
	v_mov_b64_e32 v[114:115], 0
	v_mov_b64_e32 v[116:117], 0
	v_mov_b64_e32 v[118:119], 0
	v_mov_b64_e32 v[120:121], 0
	v_mov_b64_e32 v[122:123], 0
	v_mov_b64_e32 v[124:125], 0
	v_mov_b64_e32 v[126:127], 0

.LBB0_949:
	s_add_u32 s6, s20, s38
	s_addc_u32 s7, s21, s39
	s_and_b64 s[4:5], s[12:13], exec
	v_readlane_b32 s4, v255, 24
	s_cselect_b32 s59, s7, s3
	s_cselect_b32 s58, s6, s2
	v_readlane_b32 s5, v255, 25
	s_add_u32 s6, s4, s52
	s_addc_u32 s7, s5, s53
	s_and_b64 s[4:5], s[12:13], exec
	s_cselect_b32 s61, s7, s17
	s_cselect_b32 s60, s6, s16
	v_mov_b32_e32 v161, 0
	s_and_b64 vcc, exec, s[10:11]
	v_mov_b32_e32 v160, 0
	v_mov_b32_e32 v163, 0
	v_mov_b32_e32 v162, 0
	v_mov_b32_e32 v159, 0
	v_mov_b32_e32 v158, 0
	v_mov_b32_e32 v157, 0
	v_mov_b32_e32 v156, 0
	v_mov_b32_e32 v139, 0
	v_mov_b32_e32 v138, 0
	v_mov_b32_e32 v141, 0
	v_mov_b32_e32 v140, 0
	v_mov_b32_e32 v143, 0
	v_mov_b32_e32 v142, 0
	v_mov_b32_e32 v145, 0
	v_mov_b32_e32 v144, 0
	v_mov_b32_e32 v121, 0
	v_mov_b32_e32 v120, 0
	v_mov_b32_e32 v119, 0
	v_mov_b32_e32 v118, 0
	v_mov_b32_e32 v117, 0
	v_mov_b32_e32 v116, 0
	v_mov_b32_e32 v115, 0
	v_mov_b32_e32 v114, 0
	v_mov_b32_e32 v97, 0
	v_mov_b32_e32 v96, 0
	v_mov_b32_e32 v99, 0
	v_mov_b32_e32 v98, 0
	v_mov_b32_e32 v101, 0
	v_mov_b32_e32 v100, 0
	v_mov_b32_e32 v103, 0
	v_mov_b32_e32 v102, 0
	v_mov_b32_e32 v171, 0
	v_mov_b32_e32 v170, 0
	v_mov_b32_e32 v169, 0
	v_mov_b32_e32 v168, 0
	v_mov_b32_e32 v167, 0
	v_mov_b32_e32 v166, 0
	v_mov_b32_e32 v165, 0
	v_mov_b32_e32 v164, 0
	v_mov_b32_e32 v147, 0
	v_mov_b32_e32 v146, 0
	v_mov_b32_e32 v149, 0
	v_mov_b32_e32 v148, 0
	v_mov_b32_e32 v151, 0
	v_mov_b32_e32 v150, 0
	v_mov_b32_e32 v153, 0
	v_mov_b32_e32 v152, 0
	v_mov_b32_e32 v137, 0
	v_mov_b32_e32 v136, 0
	v_mov_b32_e32 v127, 0
	v_mov_b32_e32 v126, 0
	v_mov_b32_e32 v125, 0
	v_mov_b32_e32 v124, 0
	v_mov_b32_e32 v123, 0
	v_mov_b32_e32 v122, 0
	v_mov_b32_e32 v105, 0
	v_mov_b32_e32 v104, 0
	v_mov_b32_e32 v107, 0
	v_mov_b32_e32 v106, 0
	v_mov_b32_e32 v109, 0
	v_mov_b32_e32 v108, 0
	v_mov_b32_e32 v111, 0
	v_mov_b32_e32 v110, 0
	v_mov_b32_e32 v87, 0
	v_mov_b32_e32 v86, 0
	v_mov_b32_e32 v85, 0
	v_mov_b32_e32 v84, 0
	v_mov_b32_e32 v83, 0
	v_mov_b32_e32 v82, 0
	v_mov_b32_e32 v81, 0
	v_mov_b32_e32 v80, 0
	v_mov_b32_e32 v65, 0
	v_mov_b32_e32 v64, 0
	v_mov_b32_e32 v67, 0
	v_mov_b32_e32 v66, 0
	v_mov_b32_e32 v69, 0
	v_mov_b32_e32 v68, 0
	v_mov_b32_e32 v71, 0
	v_mov_b32_e32 v70, 0
	v_mov_b32_e32 v55, 0
	v_mov_b32_e32 v54, 0
	v_mov_b32_e32 v53, 0
	v_mov_b32_e32 v52, 0
	v_mov_b32_e32 v51, 0
	v_mov_b32_e32 v50, 0
	v_mov_b32_e32 v49, 0
	v_mov_b32_e32 v48, 0
	v_mov_b32_e32 v33, 0
	v_mov_b32_e32 v32, 0
	v_mov_b32_e32 v35, 0
	v_mov_b32_e32 v34, 0
	v_mov_b32_e32 v37, 0
	v_mov_b32_e32 v36, 0
	v_mov_b32_e32 v39, 0
	v_mov_b32_e32 v38, 0
	v_mov_b32_e32 v95, 0
	v_mov_b32_e32 v94, 0
	v_mov_b32_e32 v93, 0
	v_mov_b32_e32 v92, 0
	v_mov_b32_e32 v91, 0
	v_mov_b32_e32 v90, 0
	v_mov_b32_e32 v89, 0
	v_mov_b32_e32 v88, 0
	v_mov_b32_e32 v73, 0
	v_mov_b32_e32 v72, 0
	v_mov_b32_e32 v75, 0
	v_mov_b32_e32 v74, 0
	v_mov_b32_e32 v77, 0
	v_mov_b32_e32 v76, 0
	v_mov_b32_e32 v79, 0
	v_mov_b32_e32 v78, 0
	v_mov_b32_e32 v63, 0
	v_mov_b32_e32 v62, 0
	v_mov_b32_e32 v61, 0
	v_mov_b32_e32 v60, 0
	v_mov_b32_e32 v59, 0
	v_mov_b32_e32 v58, 0
	v_mov_b32_e32 v57, 0
	v_mov_b32_e32 v56, 0
	v_mov_b32_e32 v41, 0
	v_mov_b32_e32 v40, 0
	v_mov_b32_e32 v43, 0
	v_mov_b32_e32 v42, 0
	v_mov_b32_e32 v45, 0
	v_mov_b32_e32 v44, 0
	v_mov_b32_e32 v47, 0
	v_mov_b32_e32 v46, 0
	s_cbranch_vccnz .LBB0_953
	v_mov_b64_e32 v[0:1], 0
	s_mov_b32 s4, 0
	s_mov_b64 s[36:37], 0
	v_mov_b64_e32 v[2:3], 0
	v_mov_b64_e32 v[4:5], 0
	v_mov_b64_e32 v[6:7], 0
	v_mov_b64_e32 v[8:9], 0
	v_mov_b64_e32 v[10:11], 0
	v_mov_b64_e32 v[12:13], 0
	v_mov_b64_e32 v[14:15], 0
	v_mov_b64_e32 v[16:17], 0
	v_mov_b64_e32 v[18:19], 0
	v_mov_b64_e32 v[20:21], 0
	v_mov_b64_e32 v[22:23], 0
	v_mov_b64_e32 v[24:25], 0
	v_mov_b64_e32 v[26:27], 0
	v_mov_b64_e32 v[28:29], 0
	v_mov_b64_e32 v[30:31], 0
	v_mov_b64_e32 v[32:33], 0
	v_mov_b64_e32 v[34:35], 0
	v_mov_b64_e32 v[36:37], 0
	v_mov_b64_e32 v[38:39], 0
	v_mov_b64_e32 v[40:41], 0
	v_mov_b64_e32 v[42:43], 0
	v_mov_b64_e32 v[44:45], 0
	v_mov_b64_e32 v[46:47], 0
	v_mov_b64_e32 v[48:49], 0
	v_mov_b64_e32 v[50:51], 0
	v_mov_b64_e32 v[52:53], 0
	v_mov_b64_e32 v[54:55], 0
	v_mov_b64_e32 v[56:57], 0
	v_mov_b64_e32 v[58:59], 0
	v_mov_b64_e32 v[60:61], 0
	v_mov_b64_e32 v[62:63], 0
	v_mov_b64_e32 v[64:65], 0
	v_mov_b64_e32 v[66:67], 0
	v_mov_b64_e32 v[68:69], 0
	v_mov_b64_e32 v[70:71], 0
	v_mov_b64_e32 v[72:73], 0
	v_mov_b64_e32 v[74:75], 0
	v_mov_b64_e32 v[76:77], 0
	v_mov_b64_e32 v[78:79], 0
	v_mov_b64_e32 v[80:81], 0
	v_mov_b64_e32 v[82:83], 0
	v_mov_b64_e32 v[84:85], 0
	v_mov_b64_e32 v[86:87], 0
	v_mov_b64_e32 v[88:89], 0
	v_mov_b64_e32 v[90:91], 0
	v_mov_b64_e32 v[92:93], 0
	v_mov_b64_e32 v[94:95], 0
	v_mov_b64_e32 v[96:97], 0
	v_mov_b64_e32 v[98:99], 0
	v_mov_b64_e32 v[100:101], 0
	v_mov_b64_e32 v[102:103], 0
	v_mov_b64_e32 v[104:105], 0
	v_mov_b64_e32 v[106:107], 0
	v_mov_b64_e32 v[108:109], 0
	v_mov_b64_e32 v[110:111], 0
	v_mov_b64_e32 v[112:113], 0
	v_mov_b64_e32 v[114:115], 0
	v_mov_b64_e32 v[116:117], 0
	v_mov_b64_e32 v[118:119], 0
	v_mov_b64_e32 v[120:121], 0
	v_mov_b64_e32 v[122:123], 0
	v_mov_b64_e32 v[124:125], 0
	v_mov_b64_e32 v[126:127], 0

.Lcoldzero_2:
	v_mov_b32_e32 v122, v123
	v_mov_b32_e32 v121, v123
	v_mov_b32_e32 v120, v123
	v_mov_b32_e32 v127, v123
	v_mov_b32_e32 v126, v123
	v_mov_b32_e32 v125, v123
	v_mov_b32_e32 v124, v123
	v_mov_b32_e32 v111, v123
	v_mov_b32_e32 v110, v123
	v_mov_b32_e32 v109, v123
	v_mov_b32_e32 v108, v123
	v_mov_b32_e32 v107, v123
	v_mov_b32_e32 v106, v123
	v_mov_b32_e32 v105, v123
	v_mov_b32_e32 v104, v123
	v_mov_b32_e32 v95, v123
	v_mov_b32_e32 v94, v123
	v_mov_b32_e32 v93, v123
	v_mov_b32_e32 v92, v123
	v_mov_b32_e32 v91, v123
	v_mov_b32_e32 v90, v123
	v_mov_b32_e32 v89, v123
	v_mov_b32_e32 v88, v123
	v_mov_b32_e32 v79, v123
	v_mov_b32_e32 v78, v123
	v_mov_b32_e32 v77, v123
	v_mov_b32_e32 v76, v123
	v_mov_b32_e32 v75, v123
	v_mov_b32_e32 v74, v123
	v_mov_b32_e32 v73, v123
	v_mov_b32_e32 v72, v123
	v_mov_b32_e32 v119, v123
	v_mov_b32_e32 v118, v123
	v_mov_b32_e32 v117, v123
	v_mov_b32_e32 v116, v123
	v_mov_b32_e32 v115, v123
	v_mov_b32_e32 v114, v123
	v_mov_b32_e32 v113, v123
	v_mov_b32_e32 v112, v123
	v_mov_b32_e32 v103, v123
	v_mov_b32_e32 v102, v123
	v_mov_b32_e32 v101, v123
	v_mov_b32_e32 v100, v123
	v_mov_b32_e32 v99, v123
	v_mov_b32_e32 v98, v123
	v_mov_b32_e32 v97, v123
	v_mov_b32_e32 v96, v123
	v_mov_b32_e32 v87, v123
	v_mov_b32_e32 v86, v123
	v_mov_b32_e32 v85, v123
	v_mov_b32_e32 v84, v123
	v_mov_b32_e32 v83, v123
	v_mov_b32_e32 v82, v123
	v_mov_b32_e32 v81, v123
	v_mov_b32_e32 v80, v123
	v_mov_b32_e32 v71, v123
	v_mov_b32_e32 v70, v123
	v_mov_b32_e32 v69, v123
	v_mov_b32_e32 v68, v123
	v_mov_b32_e32 v67, v123
	v_mov_b32_e32 v66, v123
	v_mov_b32_e32 v65, v123
	v_mov_b32_e32 v64, v123
	v_mov_b32_e32 v63, v123
	v_mov_b32_e32 v62, v123
	v_mov_b32_e32 v61, v123
	v_mov_b32_e32 v60, v123
	v_mov_b32_e32 v59, v123
	v_mov_b32_e32 v58, v123
	v_mov_b32_e32 v57, v123
	v_mov_b32_e32 v56, v123
	v_mov_b32_e32 v47, v123
	v_mov_b32_e32 v46, v123
	v_mov_b32_e32 v45, v123
	v_mov_b32_e32 v44, v123
	v_mov_b32_e32 v43, v123
	v_mov_b32_e32 v42, v123
	v_mov_b32_e32 v41, v123
	v_mov_b32_e32 v40, v123
	v_mov_b32_e32 v31, v123
	v_mov_b32_e32 v30, v123
	v_mov_b32_e32 v29, v123
	v_mov_b32_e32 v28, v123
	v_mov_b32_e32 v27, v123
	v_mov_b32_e32 v26, v123
	v_mov_b32_e32 v25, v123
	v_mov_b32_e32 v24, v123
	v_mov_b32_e32 v15, v123
	v_mov_b32_e32 v14, v123
	v_mov_b32_e32 v13, v123
	v_mov_b32_e32 v12, v123
	v_mov_b32_e32 v11, v123
	v_mov_b32_e32 v10, v123
	v_mov_b32_e32 v9, v123
	v_mov_b32_e32 v8, v123
	v_mov_b32_e32 v55, v123
	v_mov_b32_e32 v54, v123
	v_mov_b32_e32 v53, v123
	v_mov_b32_e32 v52, v123
	v_mov_b32_e32 v51, v123
	v_mov_b32_e32 v50, v123
	v_mov_b32_e32 v49, v123
	v_mov_b32_e32 v48, v123
	v_mov_b32_e32 v39, v123
	v_mov_b32_e32 v38, v123
	v_mov_b32_e32 v37, v123
	v_mov_b32_e32 v36, v123
	v_mov_b32_e32 v35, v123
	v_mov_b32_e32 v34, v123
	v_mov_b32_e32 v33, v123
	v_mov_b32_e32 v32, v123
	v_mov_b32_e32 v23, v123
	v_mov_b32_e32 v22, v123
	v_mov_b32_e32 v21, v123
	v_mov_b32_e32 v20, v123
	v_mov_b32_e32 v19, v123
	v_mov_b32_e32 v18, v123
	v_mov_b32_e32 v17, v123
	v_mov_b32_e32 v16, v123
	v_mov_b32_e32 v7, v123
	v_mov_b32_e32 v6, v123
	v_mov_b32_e32 v5, v123
	v_mov_b32_e32 v4, v123
	v_mov_b32_e32 v3, v123
	v_mov_b32_e32 v2, v123
	v_mov_b32_e32 v1, v123
	v_mov_b32_e32 v0, v123
	s_branch .LBB0_1194

.LBB0_1191:
	v_readlane_b32 s4, v255, 50
	v_readlane_b32 s5, v255, 51
	s_add_u32 s6, s4, s76
	s_addc_u32 s7, s5, s77
	s_and_b64 s[4:5], s[10:11], exec
	v_readlane_b32 s4, v255, 2
	s_cselect_b32 s81, s7, s3
	s_cselect_b32 s80, s6, s2
	v_readlane_b32 s5, v255, 3
	s_add_u32 s6, s4, s78
	s_addc_u32 s7, s5, s79
	s_and_b64 s[4:5], s[10:11], exec
	v_mov_b32_e32 v123, 0
	s_cselect_b32 s83, s7, s13
	s_cselect_b32 s82, s6, s12
	s_andn2_b64 vcc, exec, s[66:67]
	s_cbranch_vccnz .Lcoldzero_2
	v_mov_b64_e32 v[0:1], 0
	s_mov_b32 s4, 0
	s_mov_b64 s[14:15], 0
	v_mov_b64_e32 v[2:3], 0
	v_mov_b64_e32 v[4:5], 0
	v_mov_b64_e32 v[6:7], 0
	v_mov_b64_e32 v[8:9], 0
	v_mov_b64_e32 v[10:11], 0
	v_mov_b64_e32 v[12:13], 0
	v_mov_b64_e32 v[14:15], 0
	v_mov_b64_e32 v[16:17], 0
	v_mov_b64_e32 v[18:19], 0
	v_mov_b64_e32 v[20:21], 0
	v_mov_b64_e32 v[22:23], 0
	v_mov_b64_e32 v[24:25], 0
	v_mov_b64_e32 v[26:27], 0
	v_mov_b64_e32 v[28:29], 0
	v_mov_b64_e32 v[30:31], 0
	v_mov_b64_e32 v[32:33], 0
	v_mov_b64_e32 v[34:35], 0
	v_mov_b64_e32 v[36:37], 0
	v_mov_b64_e32 v[38:39], 0
	v_mov_b64_e32 v[40:41], 0
	v_mov_b64_e32 v[42:43], 0
	v_mov_b64_e32 v[44:45], 0
	v_mov_b64_e32 v[46:47], 0
	v_mov_b64_e32 v[48:49], 0
	v_mov_b64_e32 v[50:51], 0
	v_mov_b64_e32 v[52:53], 0
	v_mov_b64_e32 v[54:55], 0
	v_mov_b64_e32 v[56:57], 0
	v_mov_b64_e32 v[58:59], 0
	v_mov_b64_e32 v[60:61], 0
	v_mov_b64_e32 v[62:63], 0
	v_mov_b64_e32 v[64:65], 0
	v_mov_b64_e32 v[66:67], 0
	v_mov_b64_e32 v[68:69], 0
	v_mov_b64_e32 v[70:71], 0
	v_mov_b64_e32 v[72:73], 0
	v_mov_b64_e32 v[74:75], 0
	v_mov_b64_e32 v[76:77], 0
	v_mov_b64_e32 v[78:79], 0
	v_mov_b64_e32 v[80:81], 0
	v_mov_b64_e32 v[82:83], 0
	v_mov_b64_e32 v[84:85], 0
	v_mov_b64_e32 v[86:87], 0
	v_mov_b64_e32 v[88:89], 0
	v_mov_b64_e32 v[90:91], 0
	v_mov_b64_e32 v[92:93], 0
	v_mov_b64_e32 v[94:95], 0
	v_mov_b64_e32 v[96:97], 0
	v_mov_b64_e32 v[98:99], 0
	v_mov_b64_e32 v[100:101], 0
	v_mov_b64_e32 v[102:103], 0
	v_mov_b64_e32 v[104:105], 0
	v_mov_b64_e32 v[106:107], 0
	v_mov_b64_e32 v[108:109], 0
	v_mov_b64_e32 v[110:111], 0
	v_mov_b64_e32 v[112:113], 0
	v_mov_b64_e32 v[114:115], 0
	v_mov_b64_e32 v[116:117], 0
	v_mov_b64_e32 v[118:119], 0
	v_mov_b64_e32 v[120:121], 0
	v_mov_b64_e32 v[122:123], 0
	v_mov_b64_e32 v[124:125], 0
	v_mov_b64_e32 v[126:127], 0

.LBB0_1247:
	v_readlane_b32 s4, v255, 6
	v_readlane_b32 s5, v255, 7
	s_add_u32 s6, s4, s58
	s_addc_u32 s7, s5, s59
	s_and_b64 s[4:5], s[12:13], exec
	v_readlane_b32 s4, v255, 50
	s_cselect_b32 s63, s7, s67
	s_cselect_b32 s62, s6, s66
	v_readlane_b32 s5, v255, 51
	s_add_u32 s6, s4, s60
	s_addc_u32 s7, s5, s61
	s_and_b64 s[4:5], s[12:13], exec
	s_cselect_b32 s65, s7, s69
	s_cselect_b32 s64, s6, s68
	v_mov_b32_e32 v127, 0
	s_and_b64 vcc, exec, s[10:11]
	v_mov_b32_e32 v126, 0
	v_mov_b32_e32 v125, 0
	v_mov_b32_e32 v124, 0
	v_mov_b32_e32 v123, 0
	v_mov_b32_e32 v122, 0
	v_mov_b32_e32 v121, 0
	v_mov_b32_e32 v120, 0
	v_mov_b32_e32 v101, 0
	v_mov_b32_e32 v100, 0
	v_mov_b32_e32 v103, 0
	v_mov_b32_e32 v102, 0
	v_mov_b32_e32 v109, 0
	v_mov_b32_e32 v108, 0
	v_mov_b32_e32 v111, 0
	v_mov_b32_e32 v110, 0
	v_mov_b32_e32 v85, 0
	v_mov_b32_e32 v84, 0
	v_mov_b32_e32 v87, 0
	v_mov_b32_e32 v86, 0
	v_mov_b32_e32 v93, 0
	v_mov_b32_e32 v92, 0
	v_mov_b32_e32 v95, 0
	v_mov_b32_e32 v94, 0
	v_mov_b32_e32 v73, 0
	v_mov_b32_e32 v72, 0
	v_mov_b32_e32 v75, 0
	v_mov_b32_e32 v74, 0
	v_mov_b32_e32 v77, 0
	v_mov_b32_e32 v76, 0
	v_mov_b32_e32 v79, 0
	v_mov_b32_e32 v78, 0
	v_mov_b32_e32 v141, 0
	v_mov_b32_e32 v140, 0
	v_mov_b32_e32 v143, 0
	v_mov_b32_e32 v142, 0
	v_mov_b32_e32 v145, 0
	v_mov_b32_e32 v144, 0
	v_mov_b32_e32 v147, 0
	v_mov_b32_e32 v146, 0
	v_mov_b32_e32 v113, 0
	v_mov_b32_e32 v112, 0
	v_mov_b32_e32 v115, 0
	v_mov_b32_e32 v114, 0
	v_mov_b32_e32 v117, 0
	v_mov_b32_e32 v116, 0
	v_mov_b32_e32 v119, 0
	v_mov_b32_e32 v118, 0
	v_mov_b32_e32 v97, 0
	v_mov_b32_e32 v96, 0
	v_mov_b32_e32 v99, 0
	v_mov_b32_e32 v98, 0
	v_mov_b32_e32 v105, 0
	v_mov_b32_e32 v104, 0
	v_mov_b32_e32 v107, 0
	v_mov_b32_e32 v106, 0
	v_mov_b32_e32 v71, 0
	v_mov_b32_e32 v70, 0
	v_mov_b32_e32 v69, 0
	v_mov_b32_e32 v68, 0
	v_mov_b32_e32 v67, 0
	v_mov_b32_e32 v66, 0
	v_mov_b32_e32 v65, 0
	v_mov_b32_e32 v64, 0
	v_mov_b32_e32 v63, 0
	v_mov_b32_e32 v62, 0
	v_mov_b32_e32 v61, 0
	v_mov_b32_e32 v60, 0
	v_mov_b32_e32 v59, 0
	v_mov_b32_e32 v58, 0
	v_mov_b32_e32 v57, 0
	v_mov_b32_e32 v56, 0
	v_mov_b32_e32 v37, 0
	v_mov_b32_e32 v36, 0
	v_mov_b32_e32 v39, 0
	v_mov_b32_e32 v38, 0
	v_mov_b32_e32 v45, 0
	v_mov_b32_e32 v44, 0
	v_mov_b32_e32 v47, 0
	v_mov_b32_e32 v46, 0
	v_mov_b32_e32 v21, 0
	v_mov_b32_e32 v20, 0
	v_mov_b32_e32 v23, 0
	v_mov_b32_e32 v22, 0
	v_mov_b32_e32 v29, 0
	v_mov_b32_e32 v28, 0
	v_mov_b32_e32 v31, 0
	v_mov_b32_e32 v30, 0
	v_mov_b32_e32 v9, 0
	v_mov_b32_e32 v8, 0
	v_mov_b32_e32 v11, 0
	v_mov_b32_e32 v10, 0
	v_mov_b32_e32 v13, 0
	v_mov_b32_e32 v12, 0
	v_mov_b32_e32 v15, 0
	v_mov_b32_e32 v14, 0
	v_mov_b32_e32 v81, 0
	v_mov_b32_e32 v80, 0
	v_mov_b32_e32 v83, 0
	v_mov_b32_e32 v82, 0
	v_mov_b32_e32 v89, 0
	v_mov_b32_e32 v88, 0
	v_mov_b32_e32 v91, 0
	v_mov_b32_e32 v90, 0
	v_mov_b32_e32 v49, 0
	v_mov_b32_e32 v48, 0
	v_mov_b32_e32 v51, 0
	v_mov_b32_e32 v50, 0
	v_mov_b32_e32 v53, 0
	v_mov_b32_e32 v52, 0
	v_mov_b32_e32 v55, 0
	v_mov_b32_e32 v54, 0
	v_mov_b32_e32 v33, 0
	v_mov_b32_e32 v32, 0
	v_mov_b32_e32 v35, 0
	v_mov_b32_e32 v34, 0
	v_mov_b32_e32 v41, 0
	v_mov_b32_e32 v40, 0
	v_mov_b32_e32 v43, 0
	v_mov_b32_e32 v42, 0
	v_mov_b32_e32 v7, 0
	v_mov_b32_e32 v6, 0
	v_mov_b32_e32 v5, 0
	v_mov_b32_e32 v4, 0
	v_mov_b32_e32 v3, 0
	v_mov_b32_e32 v2, 0
	v_mov_b32_e32 v1, 0
	v_mov_b32_e32 v0, 0
	s_cbranch_vccnz .LBB0_1251
	v_mov_b64_e32 v[0:1], 0
	s_mov_b32 s4, 0
	s_mov_b64 s[70:71], 0
	v_mov_b64_e32 v[2:3], 0
	v_mov_b64_e32 v[4:5], 0
	v_mov_b64_e32 v[6:7], 0
	v_mov_b64_e32 v[8:9], 0
	v_mov_b64_e32 v[10:11], 0
	v_mov_b64_e32 v[12:13], 0
	v_mov_b64_e32 v[14:15], 0
	v_mov_b64_e32 v[16:17], 0
	v_mov_b64_e32 v[18:19], 0
	v_mov_b64_e32 v[20:21], 0
	v_mov_b64_e32 v[22:23], 0
	v_mov_b64_e32 v[24:25], 0
	v_mov_b64_e32 v[26:27], 0
	v_mov_b64_e32 v[28:29], 0
	v_mov_b64_e32 v[30:31], 0
	v_mov_b64_e32 v[32:33], 0
	v_mov_b64_e32 v[34:35], 0
	v_mov_b64_e32 v[36:37], 0
	v_mov_b64_e32 v[38:39], 0
	v_mov_b64_e32 v[40:41], 0
	v_mov_b64_e32 v[42:43], 0
	v_mov_b64_e32 v[44:45], 0
	v_mov_b64_e32 v[46:47], 0
	v_mov_b64_e32 v[48:49], 0
	v_mov_b64_e32 v[50:51], 0
	v_mov_b64_e32 v[52:53], 0
	v_mov_b64_e32 v[54:55], 0
	v_mov_b64_e32 v[56:57], 0
	v_mov_b64_e32 v[58:59], 0
	v_mov_b64_e32 v[60:61], 0
	v_mov_b64_e32 v[62:63], 0
	v_mov_b64_e32 v[64:65], 0
	v_mov_b64_e32 v[66:67], 0
	v_mov_b64_e32 v[68:69], 0
	v_mov_b64_e32 v[70:71], 0
	v_mov_b64_e32 v[72:73], 0
	v_mov_b64_e32 v[74:75], 0
	v_mov_b64_e32 v[76:77], 0
	v_mov_b64_e32 v[78:79], 0
	v_mov_b64_e32 v[80:81], 0
	v_mov_b64_e32 v[82:83], 0
	v_mov_b64_e32 v[84:85], 0
	v_mov_b64_e32 v[86:87], 0
	v_mov_b64_e32 v[88:89], 0
	v_mov_b64_e32 v[90:91], 0
	v_mov_b64_e32 v[92:93], 0
	v_mov_b64_e32 v[94:95], 0
	v_mov_b64_e32 v[96:97], 0
	v_mov_b64_e32 v[98:99], 0
	v_mov_b64_e32 v[100:101], 0
	v_mov_b64_e32 v[102:103], 0
	v_mov_b64_e32 v[104:105], 0
	v_mov_b64_e32 v[106:107], 0
	v_mov_b64_e32 v[108:109], 0
	v_mov_b64_e32 v[110:111], 0
	v_mov_b64_e32 v[112:113], 0
	v_mov_b64_e32 v[114:115], 0
	v_mov_b64_e32 v[116:117], 0
	v_mov_b64_e32 v[118:119], 0
	v_mov_b64_e32 v[120:121], 0
	v_mov_b64_e32 v[122:123], 0
	v_mov_b64_e32 v[124:125], 0
	v_mov_b64_e32 v[126:127], 0

.LBB0_1477:
	s_add_u32 s6, s26, s34
	s_addc_u32 s7, s27, s35
	s_and_b64 s[4:5], s[10:11], exec
	v_readlane_b32 s4, v255, 0
	s_cselect_b32 s53, s7, s37
	s_cselect_b32 s52, s6, s36
	v_readlane_b32 s5, v255, 1
	s_add_u32 s6, s4, s78
	s_addc_u32 s7, s5, s79
	s_and_b64 s[4:5], s[10:11], exec
	s_cselect_b32 s57, s7, s55
	s_cselect_b32 s56, s6, s54
	v_mov_b32_e32 v161, 0
	s_and_b64 vcc, exec, s[2:3]
	v_mov_b32_e32 v160, 0
	v_mov_b32_e32 v163, 0
	v_mov_b32_e32 v162, 0
	v_mov_b32_e32 v159, 0
	v_mov_b32_e32 v158, 0
	v_mov_b32_e32 v157, 0
	v_mov_b32_e32 v156, 0
	v_mov_b32_e32 v139, 0
	v_mov_b32_e32 v138, 0
	v_mov_b32_e32 v141, 0
	v_mov_b32_e32 v140, 0
	v_mov_b32_e32 v143, 0
	v_mov_b32_e32 v142, 0
	v_mov_b32_e32 v145, 0
	v_mov_b32_e32 v144, 0
	v_mov_b32_e32 v121, 0
	v_mov_b32_e32 v120, 0
	v_mov_b32_e32 v119, 0
	v_mov_b32_e32 v118, 0
	v_mov_b32_e32 v115, 0
	v_mov_b32_e32 v114, 0
	v_mov_b32_e32 v113, 0
	v_mov_b32_e32 v112, 0
	v_mov_b32_e32 v97, 0
	v_mov_b32_e32 v96, 0
	v_mov_b32_e32 v99, 0
	v_mov_b32_e32 v98, 0
	v_mov_b32_e32 v101, 0
	v_mov_b32_e32 v100, 0
	v_mov_b32_e32 v103, 0
	v_mov_b32_e32 v102, 0
	v_mov_b32_e32 v171, 0
	v_mov_b32_e32 v170, 0
	v_mov_b32_e32 v169, 0
	v_mov_b32_e32 v168, 0
	v_mov_b32_e32 v167, 0
	v_mov_b32_e32 v166, 0
	v_mov_b32_e32 v165, 0
	v_mov_b32_e32 v164, 0
	v_mov_b32_e32 v147, 0
	v_mov_b32_e32 v146, 0
	v_mov_b32_e32 v149, 0
	v_mov_b32_e32 v148, 0
	v_mov_b32_e32 v151, 0
	v_mov_b32_e32 v150, 0
	v_mov_b32_e32 v153, 0
	v_mov_b32_e32 v152, 0
	v_mov_b32_e32 v137, 0
	v_mov_b32_e32 v136, 0
	v_mov_b32_e32 v127, 0
	v_mov_b32_e32 v126, 0
	v_mov_b32_e32 v125, 0
	v_mov_b32_e32 v124, 0
	v_mov_b32_e32 v123, 0
	v_mov_b32_e32 v122, 0
	v_mov_b32_e32 v105, 0
	v_mov_b32_e32 v104, 0
	v_mov_b32_e32 v107, 0
	v_mov_b32_e32 v106, 0
	v_mov_b32_e32 v109, 0
	v_mov_b32_e32 v108, 0
	v_mov_b32_e32 v111, 0
	v_mov_b32_e32 v110, 0
	v_mov_b32_e32 v87, 0
	v_mov_b32_e32 v86, 0
	v_mov_b32_e32 v85, 0
	v_mov_b32_e32 v84, 0
	v_mov_b32_e32 v83, 0
	v_mov_b32_e32 v82, 0
	v_mov_b32_e32 v81, 0
	v_mov_b32_e32 v80, 0
	v_mov_b32_e32 v65, 0
	v_mov_b32_e32 v64, 0
	v_mov_b32_e32 v67, 0
	v_mov_b32_e32 v66, 0
	v_mov_b32_e32 v69, 0
	v_mov_b32_e32 v68, 0
	v_mov_b32_e32 v71, 0
	v_mov_b32_e32 v70, 0
	v_mov_b32_e32 v55, 0
	v_mov_b32_e32 v54, 0
	v_mov_b32_e32 v53, 0
	v_mov_b32_e32 v52, 0
	v_mov_b32_e32 v51, 0
	v_mov_b32_e32 v50, 0
	v_mov_b32_e32 v49, 0
	v_mov_b32_e32 v48, 0
	v_mov_b32_e32 v33, 0
	v_mov_b32_e32 v32, 0
	v_mov_b32_e32 v35, 0
	v_mov_b32_e32 v34, 0
	v_mov_b32_e32 v37, 0
	v_mov_b32_e32 v36, 0
	v_mov_b32_e32 v39, 0
	v_mov_b32_e32 v38, 0
	v_mov_b32_e32 v95, 0
	v_mov_b32_e32 v94, 0
	v_mov_b32_e32 v93, 0
	v_mov_b32_e32 v92, 0
	v_mov_b32_e32 v91, 0
	v_mov_b32_e32 v90, 0
	v_mov_b32_e32 v89, 0
	v_mov_b32_e32 v88, 0
	v_mov_b32_e32 v73, 0
	v_mov_b32_e32 v72, 0
	v_mov_b32_e32 v75, 0
	v_mov_b32_e32 v74, 0
	v_mov_b32_e32 v77, 0
	v_mov_b32_e32 v76, 0
	v_mov_b32_e32 v79, 0
	v_mov_b32_e32 v78, 0
	v_mov_b32_e32 v63, 0
	v_mov_b32_e32 v62, 0
	v_mov_b32_e32 v61, 0
	v_mov_b32_e32 v60, 0
	v_mov_b32_e32 v59, 0
	v_mov_b32_e32 v58, 0
	v_mov_b32_e32 v57, 0
	v_mov_b32_e32 v56, 0
	v_mov_b32_e32 v41, 0
	v_mov_b32_e32 v40, 0
	v_mov_b32_e32 v43, 0
	v_mov_b32_e32 v42, 0
	v_mov_b32_e32 v45, 0
	v_mov_b32_e32 v44, 0
	v_mov_b32_e32 v47, 0
	v_mov_b32_e32 v46, 0
	s_cbranch_vccnz .LBB0_1481
	v_mov_b64_e32 v[0:1], 0
	s_mov_b32 s4, 0
	s_mov_b64 s[58:59], 0
	v_mov_b64_e32 v[2:3], 0
	v_mov_b64_e32 v[4:5], 0
	v_mov_b64_e32 v[6:7], 0
	v_mov_b64_e32 v[8:9], 0
	v_mov_b64_e32 v[10:11], 0
	v_mov_b64_e32 v[12:13], 0
	v_mov_b64_e32 v[14:15], 0
	v_mov_b64_e32 v[16:17], 0
	v_mov_b64_e32 v[18:19], 0
	v_mov_b64_e32 v[20:21], 0
	v_mov_b64_e32 v[22:23], 0
	v_mov_b64_e32 v[24:25], 0
	v_mov_b64_e32 v[26:27], 0
	v_mov_b64_e32 v[28:29], 0
	v_mov_b64_e32 v[30:31], 0
	v_mov_b64_e32 v[32:33], 0
	v_mov_b64_e32 v[34:35], 0
	v_mov_b64_e32 v[36:37], 0
	v_mov_b64_e32 v[38:39], 0
	v_mov_b64_e32 v[40:41], 0
	v_mov_b64_e32 v[42:43], 0
	v_mov_b64_e32 v[44:45], 0
	v_mov_b64_e32 v[46:47], 0
	v_mov_b64_e32 v[48:49], 0
	v_mov_b64_e32 v[50:51], 0
	v_mov_b64_e32 v[52:53], 0
	v_mov_b64_e32 v[54:55], 0
	v_mov_b64_e32 v[56:57], 0
	v_mov_b64_e32 v[58:59], 0
	v_mov_b64_e32 v[60:61], 0
	v_mov_b64_e32 v[62:63], 0
	v_mov_b64_e32 v[64:65], 0
	v_mov_b64_e32 v[66:67], 0
	v_mov_b64_e32 v[68:69], 0
	v_mov_b64_e32 v[70:71], 0
	v_mov_b64_e32 v[72:73], 0
	v_mov_b64_e32 v[74:75], 0
	v_mov_b64_e32 v[76:77], 0
	v_mov_b64_e32 v[78:79], 0
	v_mov_b64_e32 v[80:81], 0
	v_mov_b64_e32 v[82:83], 0
	v_mov_b64_e32 v[84:85], 0
	v_mov_b64_e32 v[86:87], 0
	v_mov_b64_e32 v[88:89], 0
	v_mov_b64_e32 v[90:91], 0
	v_mov_b64_e32 v[92:93], 0
	v_mov_b64_e32 v[94:95], 0
	v_mov_b64_e32 v[96:97], 0
	v_mov_b64_e32 v[98:99], 0
	v_mov_b64_e32 v[100:101], 0
	v_mov_b64_e32 v[102:103], 0
	v_mov_b64_e32 v[104:105], 0
	v_mov_b64_e32 v[106:107], 0
	v_mov_b64_e32 v[108:109], 0
	v_mov_b64_e32 v[110:111], 0
	v_mov_b64_e32 v[112:113], 0
	v_mov_b64_e32 v[114:115], 0
	v_mov_b64_e32 v[116:117], 0
	v_mov_b64_e32 v[118:119], 0
	v_mov_b64_e32 v[120:121], 0
	v_mov_b64_e32 v[122:123], 0
	v_mov_b64_e32 v[124:125], 0
	v_mov_b64_e32 v[126:127], 0

.Lcoldzero_3:
	v_mov_b32_e32 v126, v127
	v_mov_b32_e32 v125, v127
	v_mov_b32_e32 v124, v127
	v_mov_b32_e32 v119, v127
	v_mov_b32_e32 v118, v127
	v_mov_b32_e32 v117, v127
	v_mov_b32_e32 v116, v127
	v_mov_b32_e32 v111, v127
	v_mov_b32_e32 v110, v127
	v_mov_b32_e32 v109, v127
	v_mov_b32_e32 v108, v127
	v_mov_b32_e32 v103, v127
	v_mov_b32_e32 v102, v127
	v_mov_b32_e32 v101, v127
	v_mov_b32_e32 v100, v127
	v_mov_b32_e32 v95, v127
	v_mov_b32_e32 v94, v127
	v_mov_b32_e32 v93, v127
	v_mov_b32_e32 v92, v127
	v_mov_b32_e32 v87, v127
	v_mov_b32_e32 v86, v127
	v_mov_b32_e32 v85, v127
	v_mov_b32_e32 v84, v127
	v_mov_b32_e32 v79, v127
	v_mov_b32_e32 v78, v127
	v_mov_b32_e32 v77, v127
	v_mov_b32_e32 v76, v127
	v_mov_b32_e32 v71, v127
	v_mov_b32_e32 v70, v127
	v_mov_b32_e32 v69, v127
	v_mov_b32_e32 v68, v127
	v_mov_b32_e32 v123, v127
	v_mov_b32_e32 v122, v127
	v_mov_b32_e32 v121, v127
	v_mov_b32_e32 v120, v127
	v_mov_b32_e32 v115, v127
	v_mov_b32_e32 v114, v127
	v_mov_b32_e32 v113, v127
	v_mov_b32_e32 v112, v127
	v_mov_b32_e32 v107, v127
	v_mov_b32_e32 v106, v127
	v_mov_b32_e32 v105, v127
	v_mov_b32_e32 v104, v127
	v_mov_b32_e32 v99, v127
	v_mov_b32_e32 v98, v127
	v_mov_b32_e32 v97, v127
	v_mov_b32_e32 v96, v127
	v_mov_b32_e32 v91, v127
	v_mov_b32_e32 v90, v127
	v_mov_b32_e32 v89, v127
	v_mov_b32_e32 v88, v127
	v_mov_b32_e32 v83, v127
	v_mov_b32_e32 v82, v127
	v_mov_b32_e32 v81, v127
	v_mov_b32_e32 v80, v127
	v_mov_b32_e32 v75, v127
	v_mov_b32_e32 v74, v127
	v_mov_b32_e32 v73, v127
	v_mov_b32_e32 v72, v127
	v_mov_b32_e32 v67, v127
	v_mov_b32_e32 v66, v127
	v_mov_b32_e32 v65, v127
	v_mov_b32_e32 v64, v127
	v_mov_b32_e32 v63, v127
	v_mov_b32_e32 v62, v127
	v_mov_b32_e32 v61, v127
	v_mov_b32_e32 v60, v127
	v_mov_b32_e32 v55, v127
	v_mov_b32_e32 v54, v127
	v_mov_b32_e32 v53, v127
	v_mov_b32_e32 v52, v127
	v_mov_b32_e32 v47, v127
	v_mov_b32_e32 v46, v127
	v_mov_b32_e32 v45, v127
	v_mov_b32_e32 v44, v127
	v_mov_b32_e32 v39, v127
	v_mov_b32_e32 v38, v127
	v_mov_b32_e32 v37, v127
	v_mov_b32_e32 v36, v127
	v_mov_b32_e32 v31, v127
	v_mov_b32_e32 v30, v127
	v_mov_b32_e32 v29, v127
	v_mov_b32_e32 v28, v127
	v_mov_b32_e32 v23, v127
	v_mov_b32_e32 v22, v127
	v_mov_b32_e32 v21, v127
	v_mov_b32_e32 v20, v127
	v_mov_b32_e32 v15, v127
	v_mov_b32_e32 v14, v127
	v_mov_b32_e32 v13, v127
	v_mov_b32_e32 v12, v127
	v_mov_b32_e32 v7, v127
	v_mov_b32_e32 v6, v127
	v_mov_b32_e32 v5, v127
	v_mov_b32_e32 v4, v127
	v_mov_b32_e32 v59, v127
	v_mov_b32_e32 v58, v127
	v_mov_b32_e32 v57, v127
	v_mov_b32_e32 v56, v127
	v_mov_b32_e32 v51, v127
	v_mov_b32_e32 v50, v127
	v_mov_b32_e32 v49, v127
	v_mov_b32_e32 v48, v127
	v_mov_b32_e32 v43, v127
	v_mov_b32_e32 v42, v127
	v_mov_b32_e32 v41, v127
	v_mov_b32_e32 v40, v127
	v_mov_b32_e32 v35, v127
	v_mov_b32_e32 v34, v127
	v_mov_b32_e32 v33, v127
	v_mov_b32_e32 v32, v127
	v_mov_b32_e32 v27, v127
	v_mov_b32_e32 v26, v127
	v_mov_b32_e32 v25, v127
	v_mov_b32_e32 v24, v127
	v_mov_b32_e32 v19, v127
	v_mov_b32_e32 v18, v127
	v_mov_b32_e32 v17, v127
	v_mov_b32_e32 v16, v127
	v_mov_b32_e32 v11, v127
	v_mov_b32_e32 v10, v127
	v_mov_b32_e32 v9, v127
	v_mov_b32_e32 v8, v127
	v_mov_b32_e32 v3, v127
	v_mov_b32_e32 v2, v127
	v_mov_b32_e32 v1, v127
	v_mov_b32_e32 v0, v127
	s_branch .LBB0_1685

.LBB0_1682:
	v_readlane_b32 s6, v255, 50
	v_readlane_b32 s7, v255, 51
	s_add_u32 s5, s6, s44
	s_addc_u32 s8, s7, s45
	s_and_b64 s[6:7], s[10:11], exec
	s_cselect_b32 s17, s8, s55
	s_cselect_b32 s16, s5, s54
	s_add_u32 s5, s20, s46
	s_addc_u32 s8, s21, s47
	s_and_b64 s[6:7], s[10:11], exec
	v_mov_b32_e32 v127, 0
	s_cselect_b32 s37, s8, s57
	s_cselect_b32 s36, s5, s56
	s_and_b64 vcc, exec, s[2:3]
	s_cbranch_vccnz .Lcoldzero_3
	v_mov_b64_e32 v[0:1], 0
	s_mov_b32 s5, 0
	s_mov_b64 s[58:59], 0
	v_mov_b64_e32 v[2:3], 0
	v_mov_b64_e32 v[4:5], 0
	v_mov_b64_e32 v[6:7], 0
	v_mov_b64_e32 v[8:9], 0
	v_mov_b64_e32 v[10:11], 0
	v_mov_b64_e32 v[12:13], 0
	v_mov_b64_e32 v[14:15], 0
	v_mov_b64_e32 v[16:17], 0
	v_mov_b64_e32 v[18:19], 0
	v_mov_b64_e32 v[20:21], 0
	v_mov_b64_e32 v[22:23], 0
	v_mov_b64_e32 v[24:25], 0
	v_mov_b64_e32 v[26:27], 0
	v_mov_b64_e32 v[28:29], 0
	v_mov_b64_e32 v[30:31], 0
	v_mov_b64_e32 v[32:33], 0
	v_mov_b64_e32 v[34:35], 0
	v_mov_b64_e32 v[36:37], 0
	v_mov_b64_e32 v[38:39], 0
	v_mov_b64_e32 v[40:41], 0
	v_mov_b64_e32 v[42:43], 0
	v_mov_b64_e32 v[44:45], 0
	v_mov_b64_e32 v[46:47], 0
	v_mov_b64_e32 v[48:49], 0
	v_mov_b64_e32 v[50:51], 0
	v_mov_b64_e32 v[52:53], 0
	v_mov_b64_e32 v[54:55], 0
	v_mov_b64_e32 v[56:57], 0
	v_mov_b64_e32 v[58:59], 0
	v_mov_b64_e32 v[60:61], 0
	v_mov_b64_e32 v[62:63], 0
	v_mov_b64_e32 v[64:65], 0
	v_mov_b64_e32 v[66:67], 0
	v_mov_b64_e32 v[68:69], 0
	v_mov_b64_e32 v[70:71], 0
	v_mov_b64_e32 v[72:73], 0
	v_mov_b64_e32 v[74:75], 0
	v_mov_b64_e32 v[76:77], 0
	v_mov_b64_e32 v[78:79], 0
	v_mov_b64_e32 v[80:81], 0
	v_mov_b64_e32 v[82:83], 0
	v_mov_b64_e32 v[84:85], 0
	v_mov_b64_e32 v[86:87], 0
	v_mov_b64_e32 v[88:89], 0
	v_mov_b64_e32 v[90:91], 0
	v_mov_b64_e32 v[92:93], 0
	v_mov_b64_e32 v[94:95], 0
	v_mov_b64_e32 v[96:97], 0
	v_mov_b64_e32 v[98:99], 0
	v_mov_b64_e32 v[100:101], 0
	v_mov_b64_e32 v[102:103], 0
	v_mov_b64_e32 v[104:105], 0
	v_mov_b64_e32 v[106:107], 0
	v_mov_b64_e32 v[108:109], 0
	v_mov_b64_e32 v[110:111], 0
	v_mov_b64_e32 v[112:113], 0
	v_mov_b64_e32 v[114:115], 0
	v_mov_b64_e32 v[116:117], 0
	v_mov_b64_e32 v[118:119], 0
	v_mov_b64_e32 v[120:121], 0
	v_mov_b64_e32 v[122:123], 0
	v_mov_b64_e32 v[124:125], 0
	v_mov_b64_e32 v[126:127], 0

.LBB0_1755:
	s_add_u32 s8, s12, s20
	s_addc_u32 s9, s13, s21
	s_and_b64 s[4:5], s[6:7], exec
	s_cselect_b32 s31, s9, s17
	s_cselect_b32 s30, s8, s16
	s_add_u32 s8, s0, s28
	s_addc_u32 s9, s1, s29
	s_and_b64 s[4:5], s[6:7], exec
	s_cselect_b32 s35, s9, s37
	s_cselect_b32 s34, s8, s36
	v_mov_b32_e32 v161, 0
	s_and_b64 vcc, exec, s[2:3]
	v_mov_b32_e32 v160, 0
	v_mov_b32_e32 v163, 0
	v_mov_b32_e32 v162, 0
	v_mov_b32_e32 v159, 0
	v_mov_b32_e32 v158, 0
	v_mov_b32_e32 v157, 0
	v_mov_b32_e32 v156, 0
	v_mov_b32_e32 v139, 0
	v_mov_b32_e32 v138, 0
	v_mov_b32_e32 v141, 0
	v_mov_b32_e32 v140, 0
	v_mov_b32_e32 v143, 0
	v_mov_b32_e32 v142, 0
	v_mov_b32_e32 v145, 0
	v_mov_b32_e32 v144, 0
	v_mov_b32_e32 v121, 0
	v_mov_b32_e32 v120, 0
	v_mov_b32_e32 v119, 0
	v_mov_b32_e32 v118, 0
	v_mov_b32_e32 v115, 0
	v_mov_b32_e32 v114, 0
	v_mov_b32_e32 v113, 0
	v_mov_b32_e32 v112, 0
	v_mov_b32_e32 v97, 0
	v_mov_b32_e32 v96, 0
	v_mov_b32_e32 v99, 0
	v_mov_b32_e32 v98, 0
	v_mov_b32_e32 v101, 0
	v_mov_b32_e32 v100, 0
	v_mov_b32_e32 v103, 0
	v_mov_b32_e32 v102, 0
	v_mov_b32_e32 v171, 0
	v_mov_b32_e32 v170, 0
	v_mov_b32_e32 v169, 0
	v_mov_b32_e32 v168, 0
	v_mov_b32_e32 v167, 0
	v_mov_b32_e32 v166, 0
	v_mov_b32_e32 v165, 0
	v_mov_b32_e32 v164, 0
	v_mov_b32_e32 v147, 0
	v_mov_b32_e32 v146, 0
	v_mov_b32_e32 v149, 0
	v_mov_b32_e32 v148, 0
	v_mov_b32_e32 v151, 0
	v_mov_b32_e32 v150, 0
	v_mov_b32_e32 v153, 0
	v_mov_b32_e32 v152, 0
	v_mov_b32_e32 v137, 0
	v_mov_b32_e32 v136, 0
	v_mov_b32_e32 v127, 0
	v_mov_b32_e32 v126, 0
	v_mov_b32_e32 v125, 0
	v_mov_b32_e32 v124, 0
	v_mov_b32_e32 v123, 0
	v_mov_b32_e32 v122, 0
	v_mov_b32_e32 v105, 0
	v_mov_b32_e32 v104, 0
	v_mov_b32_e32 v107, 0
	v_mov_b32_e32 v106, 0
	v_mov_b32_e32 v109, 0
	v_mov_b32_e32 v108, 0
	v_mov_b32_e32 v111, 0
	v_mov_b32_e32 v110, 0
	v_mov_b32_e32 v87, 0
	v_mov_b32_e32 v86, 0
	v_mov_b32_e32 v85, 0
	v_mov_b32_e32 v84, 0
	v_mov_b32_e32 v83, 0
	v_mov_b32_e32 v82, 0
	v_mov_b32_e32 v81, 0
	v_mov_b32_e32 v80, 0
	v_mov_b32_e32 v65, 0
	v_mov_b32_e32 v64, 0
	v_mov_b32_e32 v67, 0
	v_mov_b32_e32 v66, 0
	v_mov_b32_e32 v69, 0
	v_mov_b32_e32 v68, 0
	v_mov_b32_e32 v71, 0
	v_mov_b32_e32 v70, 0
	v_mov_b32_e32 v55, 0
	v_mov_b32_e32 v54, 0
	v_mov_b32_e32 v53, 0
	v_mov_b32_e32 v52, 0
	v_mov_b32_e32 v51, 0
	v_mov_b32_e32 v50, 0
	v_mov_b32_e32 v49, 0
	v_mov_b32_e32 v48, 0
	v_mov_b32_e32 v33, 0
	v_mov_b32_e32 v32, 0
	v_mov_b32_e32 v35, 0
	v_mov_b32_e32 v34, 0
	v_mov_b32_e32 v37, 0
	v_mov_b32_e32 v36, 0
	v_mov_b32_e32 v39, 0
	v_mov_b32_e32 v38, 0
	v_mov_b32_e32 v95, 0
	v_mov_b32_e32 v94, 0
	v_mov_b32_e32 v93, 0
	v_mov_b32_e32 v92, 0
	v_mov_b32_e32 v91, 0
	v_mov_b32_e32 v90, 0
	v_mov_b32_e32 v89, 0
	v_mov_b32_e32 v88, 0
	v_mov_b32_e32 v73, 0
	v_mov_b32_e32 v72, 0
	v_mov_b32_e32 v75, 0
	v_mov_b32_e32 v74, 0
	v_mov_b32_e32 v77, 0
	v_mov_b32_e32 v76, 0
	v_mov_b32_e32 v79, 0
	v_mov_b32_e32 v78, 0
	v_mov_b32_e32 v63, 0
	v_mov_b32_e32 v62, 0
	v_mov_b32_e32 v61, 0
	v_mov_b32_e32 v60, 0
	v_mov_b32_e32 v59, 0
	v_mov_b32_e32 v58, 0
	v_mov_b32_e32 v57, 0
	v_mov_b32_e32 v56, 0
	v_mov_b32_e32 v41, 0
	v_mov_b32_e32 v40, 0
	v_mov_b32_e32 v43, 0
	v_mov_b32_e32 v42, 0
	v_mov_b32_e32 v45, 0
	v_mov_b32_e32 v44, 0
	v_mov_b32_e32 v47, 0
	v_mov_b32_e32 v46, 0
	s_cbranch_vccnz .LBB0_1759
	v_mov_b64_e32 v[0:1], 0
	s_mov_b32 s4, 0
	s_mov_b64 s[38:39], 0
	v_mov_b64_e32 v[2:3], 0
	v_mov_b64_e32 v[4:5], 0
	v_mov_b64_e32 v[6:7], 0
	v_mov_b64_e32 v[8:9], 0
	v_mov_b64_e32 v[10:11], 0
	v_mov_b64_e32 v[12:13], 0
	v_mov_b64_e32 v[14:15], 0
	v_mov_b64_e32 v[16:17], 0
	v_mov_b64_e32 v[18:19], 0
	v_mov_b64_e32 v[20:21], 0
	v_mov_b64_e32 v[22:23], 0
	v_mov_b64_e32 v[24:25], 0
	v_mov_b64_e32 v[26:27], 0
	v_mov_b64_e32 v[28:29], 0
	v_mov_b64_e32 v[30:31], 0
	v_mov_b64_e32 v[32:33], 0
	v_mov_b64_e32 v[34:35], 0
	v_mov_b64_e32 v[36:37], 0
	v_mov_b64_e32 v[38:39], 0
	v_mov_b64_e32 v[40:41], 0
	v_mov_b64_e32 v[42:43], 0
	v_mov_b64_e32 v[44:45], 0
	v_mov_b64_e32 v[46:47], 0
	v_mov_b64_e32 v[48:49], 0
	v_mov_b64_e32 v[50:51], 0
	v_mov_b64_e32 v[52:53], 0
	v_mov_b64_e32 v[54:55], 0
	v_mov_b64_e32 v[56:57], 0
	v_mov_b64_e32 v[58:59], 0
	v_mov_b64_e32 v[60:61], 0
	v_mov_b64_e32 v[62:63], 0
	v_mov_b64_e32 v[64:65], 0
	v_mov_b64_e32 v[66:67], 0
	v_mov_b64_e32 v[68:69], 0
	v_mov_b64_e32 v[70:71], 0
	v_mov_b64_e32 v[72:73], 0
	v_mov_b64_e32 v[74:75], 0
	v_mov_b64_e32 v[76:77], 0
	v_mov_b64_e32 v[78:79], 0
	v_mov_b64_e32 v[80:81], 0
	v_mov_b64_e32 v[82:83], 0
	v_mov_b64_e32 v[84:85], 0
	v_mov_b64_e32 v[86:87], 0
	v_mov_b64_e32 v[88:89], 0
	v_mov_b64_e32 v[90:91], 0
	v_mov_b64_e32 v[92:93], 0
	v_mov_b64_e32 v[94:95], 0
	v_mov_b64_e32 v[96:97], 0
	v_mov_b64_e32 v[98:99], 0
	v_mov_b64_e32 v[100:101], 0
	v_mov_b64_e32 v[102:103], 0
	v_mov_b64_e32 v[104:105], 0
	v_mov_b64_e32 v[106:107], 0
	v_mov_b64_e32 v[108:109], 0
	v_mov_b64_e32 v[110:111], 0
	v_mov_b64_e32 v[112:113], 0
	v_mov_b64_e32 v[114:115], 0
	v_mov_b64_e32 v[116:117], 0
	v_mov_b64_e32 v[118:119], 0
	v_mov_b64_e32 v[120:121], 0
	v_mov_b64_e32 v[122:123], 0
	v_mov_b64_e32 v[124:125], 0
	v_mov_b64_e32 v[126:127], 0
